# diff-attention steady loop: V fragments read 4 MFMA gaps ahead (4-deep rotation in dead score registers) instead of 2
# speedup vs baseline: 1.0080x; 1.0080x over previous
; #define PG8_STAGE(bufoff, gbase, voff) do { _Pragma("unroll") for (int _i = 0; _i < 2; ++_i) \
;         __builtin_amdgcn_global_load_lds((const unsigned*)((const char*)(gbase) + (voff)[_i]), (PG8_LAS unsigned*)(lds + (bufoff) + ldsw + _i * 8192), 16, 0, 0); } while (0)
; #define PG8_LDA(dst, b, h) do { _Pragma("unroll") for (int m = 0; m < 4; ++m) _Pragma("unroll") for (int k = 0; k < 2; ++k) dst[m][k] = *(const PG8_LAS bf16x8*)(lds + PG8_SA(b, h) + aoff + m * 2048 + k * 1024); } while (0)
; #define PG8_LDB(dst, b, h) do { _Pragma("unroll") for (int n = 0; n < 2; ++n) _Pragma("unroll") for (int k = 0; k < 2; ++k) dst[n][k] = *(const PG8_LAS bf16x8*)(lds + PG8_SB(b, h) + boff + n * 2048 + k * 1024); } while (0)
; #define PG8_MMA(ai, bj, At, Bt) do { __builtin_amdgcn_s_setprio(1); _Pragma("unroll") for (int m = 0; m < 4; ++m) _Pragma("unroll") for (int n = 0; n < 2; ++n) _Pragma("unroll") for (int k = 0; k < 2; ++k) \
;         acc[ai][bj][m][n] = __builtin_amdgcn_mfma_f32_16x16x32_bf16(Bt[n][k], At[m][k], acc[ai][bj][m][n], 0, 0, 0); __builtin_amdgcn_s_setprio(0); } while (0)
; #define PG8_BAR __builtin_amdgcn_s_barrier()
; template <class Epi, class Sched, bool ALIGN_EPI = false, bool SP2 = false>
; __device__ __forceinline__ void gemm_phase(PG8_LAS unsigned char* lds, const Gemm g, const Sched& S, const Epi& E, const int tid_in) {
;     ...
;             PG8_LDB(B0, 0, 0); PG8_LDB(B1, 0, 1); PG8_SCHED; PG8_LDA(At, 0, 0); PG8_STAGE(PG8_SA(1, 1), a1 + hstep, voffA);
;             PG8_WAIT_V(8); PG8_WAIT_L(0); PG8_BAR; PG8_MMA(0, 0, At, B0); PG8_MMA(0, 1, At, B1); PG8_BAR; PG8_SCHED;
;             PG8_LDA(At, 0, 1); PG8_STAGE(PG8_SB(0, 0), b2, voffB); PG8_STAGE(PG8_SB(0, 1), b2 + hstep, voffB); PG8_STAGE(PG8_SA(0, 0), a2, voffA);
;             PG8_WAIT_V(8); PG8_WAIT_L(0); PG8_BAR; PG8_MMA(1, 0, At, B0); PG8_MMA(1, 1, At, B1); PG8_BAR; PG8_SCHED;
;             PG8_LDB(B0, 1, 0); PG8_LDB(B1, 1, 1); PG8_SCHED; PG8_LDA(At, 1, 0); PG8_STAGE(PG8_SA(0, 1), a2 + hstep, voffA);
;             PG8_WAIT_V(8); PG8_WAIT_L(0); PG8_BAR; PG8_MMA(0, 0, At, B0); PG8_MMA(0, 1, At, B1); PG8_BAR; PG8_SCHED;
;             PG8_LDA(At, 1, 1); PG8_STAGE(PG8_SB(1, 0), b3, voffB); PG8_STAGE(PG8_SB(1, 1), b3 + hstep, voffB); PG8_STAGE(PG8_SA(1, 0), a3, voffA);
;             PG8_WAIT_V(8); PG8_WAIT_L(0); PG8_BAR; PG8_MMA(1, 0, At, B0); PG8_MMA(1, 1, At, B1); PG8_BAR; PG8_SCHED;
.LBB0_92:
	s_add_u32 s62, s6, 0xfffc0080
	s_addc_u32 s63, s7, -1
	s_add_i32 s64, 0, 0x10000
	s_cmp_eq_u32 s61, 12
	s_cselect_b32 s81, s11, s63
	s_cselect_b32 s80, s42, s62
	s_cselect_b32 s79, s43, s60
	s_cselect_b32 s78, s58, s59
	s_add_i32 s71, 0, 0x14000
	v_add_u32_e32 v142, s64, v171
	v_add_u32_e32 v183, s71, v171
	ds_read_b128 v[130:133], v142
	ds_read_b128 v[134:137], v142 offset:1024
	ds_read_b128 v[138:141], v142 offset:2048
	ds_read_b128 v[142:145], v142 offset:3072
	ds_read_b128 v[162:165], v183
	ds_read_b128 v[166:169], v183 offset:1024
	ds_read_b128 v[184:187], v183 offset:2048
	ds_read_b128 v[188:191], v183 offset:3072
	v_lshl_add_u64 v[224:225], s[6:7], 0, v[156:157]
	s_add_i32 m0, s26, 0xc000
	ds_read_b128 v[192:195], v174
	ds_read_b128 v[196:199], v174 offset:1024
	ds_read_b128 v[200:203], v174 offset:2048
	ds_read_b128 v[204:207], v174 offset:3072
	ds_read_b128 v[208:211], v174 offset:4096
	ds_read_b128 v[212:215], v174 offset:5120
	ds_read_b128 v[216:219], v174 offset:6144
	ds_read_b128 v[220:223], v174 offset:7168
	global_load_lds_dwordx4 v[224:225], off
	v_lshl_add_u64 v[224:225], s[6:7], 0, v[158:159]
	s_add_i32 m0, s26, 0xe000
	s_nop 0
	global_load_lds_dwordx4 v[224:225], off
	s_waitcnt vmcnt(8)
	s_waitcnt lgkmcnt(0)
	s_barrier
	s_setprio 1
	s_waitcnt lgkmcnt(0)
	v_mfma_f32_16x16x32_bf16 v[126:129], v[130:133], v[192:195], v[126:129]
	v_mfma_f32_16x16x32_bf16 v[122:125], v[138:141], v[192:195], v[122:125]
	v_mfma_f32_16x16x32_bf16 v[110:113], v[130:133], v[200:203], v[110:113]
	v_mfma_f32_16x16x32_bf16 v[106:109], v[138:141], v[200:203], v[106:109]
	v_mfma_f32_16x16x32_bf16 v[94:97], v[130:133], v[208:211], v[94:97]
	v_mfma_f32_16x16x32_bf16 v[90:93], v[138:141], v[208:211], v[90:93]
	v_mfma_f32_16x16x32_bf16 v[78:81], v[130:133], v[216:219], v[78:81]
	v_mfma_f32_16x16x32_bf16 v[74:77], v[138:141], v[216:219], v[74:77]
	v_mfma_f32_16x16x32_bf16 v[126:129], v[134:137], v[196:199], v[126:129]
	v_mfma_f32_16x16x32_bf16 v[122:125], v[142:145], v[196:199], v[122:125]
	v_mfma_f32_16x16x32_bf16 v[110:113], v[134:137], v[204:207], v[110:113]
	v_mfma_f32_16x16x32_bf16 v[106:109], v[142:145], v[204:207], v[106:109]
	v_mfma_f32_16x16x32_bf16 v[94:97], v[134:137], v[212:215], v[94:97]
	v_mfma_f32_16x16x32_bf16 v[90:93], v[142:145], v[212:215], v[90:93]
	v_mfma_f32_16x16x32_bf16 v[78:81], v[134:137], v[220:223], v[78:81]
	v_mfma_f32_16x16x32_bf16 v[74:77], v[142:145], v[220:223], v[74:77]
	s_setprio 0
	s_setprio 1
	v_mfma_f32_16x16x32_bf16 v[118:121], v[162:165], v[192:195], v[118:121]
	v_mfma_f32_16x16x32_bf16 v[114:117], v[184:187], v[192:195], v[114:117]
	v_mfma_f32_16x16x32_bf16 v[102:105], v[162:165], v[200:203], v[102:105]
	v_mfma_f32_16x16x32_bf16 v[98:101], v[184:187], v[200:203], v[98:101]
	v_mfma_f32_16x16x32_bf16 v[86:89], v[162:165], v[208:211], v[86:89]
	v_mfma_f32_16x16x32_bf16 v[82:85], v[184:187], v[208:211], v[82:85]
	v_mfma_f32_16x16x32_bf16 v[70:73], v[162:165], v[216:219], v[70:73]
	v_mfma_f32_16x16x32_bf16 v[66:69], v[184:187], v[216:219], v[66:69]
	v_mfma_f32_16x16x32_bf16 v[118:121], v[166:169], v[196:199], v[118:121]
	v_mfma_f32_16x16x32_bf16 v[114:117], v[188:191], v[196:199], v[114:117]
	v_mfma_f32_16x16x32_bf16 v[102:105], v[166:169], v[204:207], v[102:105]
	v_mfma_f32_16x16x32_bf16 v[98:101], v[188:191], v[204:207], v[98:101]
	v_mfma_f32_16x16x32_bf16 v[86:89], v[166:169], v[212:215], v[86:89]
	v_mfma_f32_16x16x32_bf16 v[82:85], v[188:191], v[212:215], v[82:85]
	v_mfma_f32_16x16x32_bf16 v[70:73], v[166:169], v[220:223], v[70:73]
	v_mfma_f32_16x16x32_bf16 v[66:69], v[188:191], v[220:223], v[66:69]
	s_setprio 0
	s_barrier
	s_add_i32 s62, s64, s21
	v_lshl_add_u64 v[224:225], s[78:79], 0, v[0:1]
	s_mov_b32 m0, s62
	ds_read_b128 v[192:195], v174 offset:16384
	ds_read_b128 v[196:199], v174 offset:17408
	ds_read_b128 v[200:203], v174 offset:18432
	ds_read_b128 v[204:207], v174 offset:19456
	ds_read_b128 v[208:211], v174 offset:20480
	ds_read_b128 v[212:215], v174 offset:21504
	ds_read_b128 v[216:219], v174 offset:22528
	ds_read_b128 v[220:223], v174 offset:23552
	global_load_lds_dwordx4 v[224:225], off
	s_add_i32 m0, s62, 0x2000
	s_add_u32 s62, s78, 0x40000
	v_lshl_add_u64 v[226:227], s[78:79], 0, v[150:151]
	s_addc_u32 s63, s79, 0
	s_add_i32 s64, s71, s21
	global_load_lds_dwordx4 v[226:227], off
	v_lshl_add_u64 v[228:229], s[62:63], 0, v[0:1]
	s_mov_b32 m0, s64
	v_lshl_add_u64 v[230:231], s[80:81], 0, v[148:149]
	global_load_lds_dwordx4 v[228:229], off
	v_lshl_add_u64 v[228:229], s[62:63], 0, v[150:151]
	s_add_i32 m0, s64, 0x2000
	s_nop 0
	global_load_lds_dwordx4 v[228:229], off
	v_lshl_add_u64 v[228:229], s[80:81], 0, v[146:147]
	s_mov_b32 m0, s26
	s_nop 0
	global_load_lds_dwordx4 v[228:229], off
	s_mov_b32 m0, s27
	s_nop 0
	global_load_lds_dwordx4 v[230:231], off
	s_waitcnt vmcnt(8)
	s_waitcnt lgkmcnt(0)
	s_barrier
; #define PG8_STAGE(bufoff, gbase, voff) do { _Pragma("unroll") for (int _i = 0; _i < 2; ++_i) \
;         __builtin_amdgcn_global_load_lds((const unsigned*)((const char*)(gbase) + (voff)[_i]), (PG8_LAS unsigned*)(lds + (bufoff) + ldsw + _i * 8192), 16, 0, 0); } while (0)
; #define PG8_LDA(dst, b, h) do { _Pragma("unroll") for (int m = 0; m < 4; ++m) _Pragma("unroll") for (int k = 0; k < 2; ++k) dst[m][k] = *(const PG8_LAS bf16x8*)(lds + PG8_SA(b, h) + aoff + m * 2048 + k * 1024); } while (0)
; #define PG8_LDB(dst, b, h) do { _Pragma("unroll") for (int n = 0; n < 2; ++n) _Pragma("unroll") for (int k = 0; k < 2; ++k) dst[n][k] = *(const PG8_LAS bf16x8*)(lds + PG8_SB(b, h) + boff + n * 2048 + k * 1024); } while (0)
; #define PG8_MMA(ai, bj, At, Bt) do { __builtin_amdgcn_s_setprio(1); _Pragma("unroll") for (int m = 0; m < 4; ++m) _Pragma("unroll") for (int n = 0; n < 2; ++n) _Pragma("unroll") for (int k = 0; k < 2; ++k) \
;         acc[ai][bj][m][n] = __builtin_amdgcn_mfma_f32_16x16x32_bf16(Bt[n][k], At[m][k], acc[ai][bj][m][n], 0, 0, 0); __builtin_amdgcn_s_setprio(0); } while (0)
; #define PG8_BAR __builtin_amdgcn_s_barrier()
; template <class Epi, class Sched, bool ALIGN_EPI = false, bool SP2 = false>
; __device__ __forceinline__ void gemm_phase(PG8_LAS unsigned char* lds, const Gemm g, const Sched& S, const Epi& E, const int tid_in) {
;     ...
;             PG8_LDB(B0, 0, 0); PG8_LDB(B1, 0, 1); PG8_SCHED; PG8_LDA(At, 0, 0); PG8_STAGE(PG8_SA(1, 1), a1 + hstep, voffA);
;             PG8_WAIT_V(8); PG8_WAIT_L(0); PG8_BAR; PG8_MMA(0, 0, At, B0); PG8_MMA(0, 1, At, B1); PG8_BAR; PG8_SCHED;
;             PG8_LDA(At, 0, 1); PG8_STAGE(PG8_SB(0, 0), b2, voffB); PG8_STAGE(PG8_SB(0, 1), b2 + hstep, voffB); PG8_STAGE(PG8_SA(0, 0), a2, voffA);
;             PG8_WAIT_V(8); PG8_WAIT_L(0); PG8_BAR; PG8_MMA(1, 0, At, B0); PG8_MMA(1, 1, At, B1); PG8_BAR; PG8_SCHED;
;             PG8_LDB(B0, 1, 0); PG8_LDB(B1, 1, 1); PG8_SCHED; PG8_LDA(At, 1, 0); PG8_STAGE(PG8_SA(0, 1), a2 + hstep, voffA);
;             PG8_WAIT_V(8); PG8_WAIT_L(0); PG8_BAR; PG8_MMA(0, 0, At, B0); PG8_MMA(0, 1, At, B1); PG8_BAR; PG8_SCHED;
;             PG8_LDA(At, 1, 1); PG8_STAGE(PG8_SB(1, 0), b3, voffB); PG8_STAGE(PG8_SB(1, 1), b3 + hstep, voffB); PG8_STAGE(PG8_SA(1, 0), a3, voffA);
;             PG8_WAIT_V(8); PG8_WAIT_L(0); PG8_BAR; PG8_MMA(1, 0, At, B0); PG8_MMA(1, 1, At, B1); PG8_BAR; PG8_SCHED;
	s_setprio 1
	s_waitcnt lgkmcnt(0)
	v_mfma_f32_16x16x32_bf16 v[62:65], v[130:133], v[192:195], v[62:65]
	v_mfma_f32_16x16x32_bf16 v[58:61], v[138:141], v[192:195], v[58:61]
	v_mfma_f32_16x16x32_bf16 v[46:49], v[130:133], v[200:203], v[46:49]
	v_mfma_f32_16x16x32_bf16 v[42:45], v[138:141], v[200:203], v[42:45]
	v_mfma_f32_16x16x32_bf16 v[30:33], v[130:133], v[208:211], v[30:33]
	v_mfma_f32_16x16x32_bf16 v[26:29], v[138:141], v[208:211], v[26:29]
	v_mfma_f32_16x16x32_bf16 v[14:17], v[130:133], v[216:219], v[14:17]
	v_mfma_f32_16x16x32_bf16 v[10:13], v[138:141], v[216:219], v[10:13]
	v_mfma_f32_16x16x32_bf16 v[62:65], v[134:137], v[196:199], v[62:65]
	v_mfma_f32_16x16x32_bf16 v[58:61], v[142:145], v[196:199], v[58:61]
	v_mfma_f32_16x16x32_bf16 v[46:49], v[134:137], v[204:207], v[46:49]
	v_mfma_f32_16x16x32_bf16 v[42:45], v[142:145], v[204:207], v[42:45]
	v_mfma_f32_16x16x32_bf16 v[30:33], v[134:137], v[212:215], v[30:33]
	v_mfma_f32_16x16x32_bf16 v[26:29], v[142:145], v[212:215], v[26:29]
	v_mfma_f32_16x16x32_bf16 v[14:17], v[134:137], v[220:223], v[14:17]
	v_mfma_f32_16x16x32_bf16 v[10:13], v[142:145], v[220:223], v[10:13]
	s_setprio 0
	s_setprio 1
	v_mfma_f32_16x16x32_bf16 v[54:57], v[162:165], v[192:195], v[54:57]
	v_mfma_f32_16x16x32_bf16 v[50:53], v[184:187], v[192:195], v[50:53]
	v_mfma_f32_16x16x32_bf16 v[38:41], v[162:165], v[200:203], v[38:41]
	v_mfma_f32_16x16x32_bf16 v[34:37], v[184:187], v[200:203], v[34:37]
	v_mfma_f32_16x16x32_bf16 v[22:25], v[162:165], v[208:211], v[22:25]
	v_mfma_f32_16x16x32_bf16 v[18:21], v[184:187], v[208:211], v[18:21]
	v_mfma_f32_16x16x32_bf16 v[6:9], v[162:165], v[216:219], v[6:9]
	v_mfma_f32_16x16x32_bf16 v[2:5], v[184:187], v[216:219], v[2:5]
	v_mfma_f32_16x16x32_bf16 v[54:57], v[166:169], v[196:199], v[54:57]
	v_mfma_f32_16x16x32_bf16 v[50:53], v[188:191], v[196:199], v[50:53]
	v_mfma_f32_16x16x32_bf16 v[38:41], v[166:169], v[204:207], v[38:41]
	v_mfma_f32_16x16x32_bf16 v[34:37], v[188:191], v[204:207], v[34:37]
	v_mfma_f32_16x16x32_bf16 v[22:25], v[166:169], v[212:215], v[22:25]
	v_mfma_f32_16x16x32_bf16 v[18:21], v[188:191], v[212:215], v[18:21]
	v_mfma_f32_16x16x32_bf16 v[6:9], v[166:169], v[220:223], v[6:9]
	v_mfma_f32_16x16x32_bf16 v[2:5], v[188:191], v[220:223], v[2:5]
	s_setprio 0
	s_barrier
	s_add_i32 s64, 0, 0x18000
	s_add_i32 s71, 0, 0x1c000
	v_add_u32_e32 v142, s64, v171
	v_add_u32_e32 v183, s71, v171
	ds_read_b128 v[130:133], v142
	ds_read_b128 v[134:137], v142 offset:1024
	ds_read_b128 v[138:141], v142 offset:2048
	ds_read_b128 v[142:145], v142 offset:3072
	ds_read_b128 v[162:165], v183
	ds_read_b128 v[166:169], v183 offset:1024
	ds_read_b128 v[184:187], v183 offset:2048
	ds_read_b128 v[188:191], v183 offset:3072
	s_add_u32 s62, s80, 0x40000
	s_addc_u32 s63, s81, 0
	s_mov_b32 m0, s29
	v_lshl_add_u64 v[232:233], s[62:63], 0, v[146:147]
	ds_read_b128 v[192:195], v174 offset:32768
	ds_read_b128 v[196:199], v174 offset:33792
	ds_read_b128 v[200:203], v174 offset:34816
	ds_read_b128 v[204:207], v174 offset:35840
	ds_read_b128 v[208:211], v174 offset:36864
	ds_read_b128 v[212:215], v174 offset:37888
	ds_read_b128 v[216:219], v174 offset:38912
	ds_read_b128 v[220:223], v174 offset:39936
	global_load_lds_dwordx4 v[232:233], off
	v_lshl_add_u64 v[232:233], s[62:63], 0, v[148:149]
	s_mov_b32 m0, s34
	s_nop 0
	global_load_lds_dwordx4 v[232:233], off
	s_waitcnt vmcnt(8)
	s_waitcnt lgkmcnt(0)
	s_barrier
	s_setprio 1
	s_waitcnt lgkmcnt(0)
	v_mfma_f32_16x16x32_bf16 v[126:129], v[130:133], v[192:195], v[126:129]
	v_mfma_f32_16x16x32_bf16 v[122:125], v[138:141], v[192:195], v[122:125]
	v_mfma_f32_16x16x32_bf16 v[110:113], v[130:133], v[200:203], v[110:113]
	v_mfma_f32_16x16x32_bf16 v[106:109], v[138:141], v[200:203], v[106:109]
	v_mfma_f32_16x16x32_bf16 v[94:97], v[130:133], v[208:211], v[94:97]
	v_mfma_f32_16x16x32_bf16 v[90:93], v[138:141], v[208:211], v[90:93]
	v_mfma_f32_16x16x32_bf16 v[78:81], v[130:133], v[216:219], v[78:81]
	v_mfma_f32_16x16x32_bf16 v[74:77], v[138:141], v[216:219], v[74:77]
	v_mfma_f32_16x16x32_bf16 v[126:129], v[134:137], v[196:199], v[126:129]
	v_mfma_f32_16x16x32_bf16 v[122:125], v[142:145], v[196:199], v[122:125]
	v_mfma_f32_16x16x32_bf16 v[110:113], v[134:137], v[204:207], v[110:113]
	v_mfma_f32_16x16x32_bf16 v[106:109], v[142:145], v[204:207], v[106:109]
	v_mfma_f32_16x16x32_bf16 v[94:97], v[134:137], v[212:215], v[94:97]
	v_mfma_f32_16x16x32_bf16 v[90:93], v[142:145], v[212:215], v[90:93]
	v_mfma_f32_16x16x32_bf16 v[78:81], v[134:137], v[220:223], v[78:81]
	v_mfma_f32_16x16x32_bf16 v[74:77], v[142:145], v[220:223], v[74:77]
	s_setprio 0
	s_setprio 1
	v_mfma_f32_16x16x32_bf16 v[118:121], v[162:165], v[192:195], v[118:121]
	v_mfma_f32_16x16x32_bf16 v[114:117], v[184:187], v[192:195], v[114:117]
	v_mfma_f32_16x16x32_bf16 v[102:105], v[162:165], v[200:203], v[102:105]
	v_mfma_f32_16x16x32_bf16 v[98:101], v[184:187], v[200:203], v[98:101]
	v_mfma_f32_16x16x32_bf16 v[86:89], v[162:165], v[208:211], v[86:89]
	v_mfma_f32_16x16x32_bf16 v[82:85], v[184:187], v[208:211], v[82:85]
	v_mfma_f32_16x16x32_bf16 v[70:73], v[162:165], v[216:219], v[70:73]
	v_mfma_f32_16x16x32_bf16 v[66:69], v[184:187], v[216:219], v[66:69]
	v_mfma_f32_16x16x32_bf16 v[118:121], v[166:169], v[196:199], v[118:121]
	v_mfma_f32_16x16x32_bf16 v[114:117], v[188:191], v[196:199], v[114:117]
	v_mfma_f32_16x16x32_bf16 v[102:105], v[166:169], v[204:207], v[102:105]
	v_mfma_f32_16x16x32_bf16 v[98:101], v[188:191], v[204:207], v[98:101]
	v_mfma_f32_16x16x32_bf16 v[86:89], v[166:169], v[212:215], v[86:89]
	v_mfma_f32_16x16x32_bf16 v[82:85], v[188:191], v[212:215], v[82:85]
	v_mfma_f32_16x16x32_bf16 v[70:73], v[166:169], v[220:223], v[70:73]
	v_mfma_f32_16x16x32_bf16 v[66:69], v[188:191], v[220:223], v[66:69]
	s_setprio 0
	s_barrier
; #define PG8_STAGE(bufoff, gbase, voff) do { _Pragma("unroll") for (int _i = 0; _i < 2; ++_i) \
;         __builtin_amdgcn_global_load_lds((const unsigned*)((const char*)(gbase) + (voff)[_i]), (PG8_LAS unsigned*)(lds + (bufoff) + ldsw + _i * 8192), 16, 0, 0); } while (0)
; #define PG8_LDA(dst, b, h) do { _Pragma("unroll") for (int m = 0; m < 4; ++m) _Pragma("unroll") for (int k = 0; k < 2; ++k) dst[m][k] = *(const PG8_LAS bf16x8*)(lds + PG8_SA(b, h) + aoff + m * 2048 + k * 1024); } while (0)
; #define PG8_MMA(ai, bj, At, Bt) do { __builtin_amdgcn_s_setprio(1); _Pragma("unroll") for (int m = 0; m < 4; ++m) _Pragma("unroll") for (int n = 0; n < 2; ++n) _Pragma("unroll") for (int k = 0; k < 2; ++k) \
;         acc[ai][bj][m][n] = __builtin_amdgcn_mfma_f32_16x16x32_bf16(Bt[n][k], At[m][k], acc[ai][bj][m][n], 0, 0, 0); __builtin_amdgcn_s_setprio(0); } while (0)
; #define PG8_WAIT_V(n) asm volatile("s_waitcnt vmcnt(" #n ")" ::: "memory")
; #define PG8_WAIT_L(n) asm volatile("s_waitcnt lgkmcnt(" #n ")" ::: "memory")
; #define PG8_BAR __builtin_amdgcn_s_barrier()
; #define PG8_SCHED __builtin_amdgcn_sched_barrier(0)
; template <class Epi, class Sched, bool ALIGN_EPI = false, bool SP2 = false>
; __device__ __forceinline__ void gemm_phase(PG8_LAS unsigned char* lds, const Gemm g, const Sched& S, const Epi& E, const int tid_in) {
;     ...
;             PG8_LDA(At, 1, 1); PG8_STAGE(PG8_SB(1, 0), b3, voffB); PG8_STAGE(PG8_SB(1, 1), b3 + hstep, voffB); PG8_STAGE(PG8_SA(1, 0), a3, voffA);
;             PG8_WAIT_V(8); PG8_WAIT_L(0); PG8_BAR; PG8_MMA(1, 0, At, B0); PG8_MMA(1, 1, At, B1); PG8_BAR; PG8_SCHED;
	s_add_i32 s62, s64, s21
	v_lshl_add_u64 v[224:225], v[224:225], 0, s[44:45]
	s_mov_b32 m0, s62
	ds_read_b128 v[192:195], v174 offset:49152
	ds_read_b128 v[196:199], v174 offset:50176
	ds_read_b128 v[200:203], v174 offset:51200
	ds_read_b128 v[204:207], v174 offset:52224
	ds_read_b128 v[208:211], v174 offset:53248
	ds_read_b128 v[212:215], v174 offset:54272
	ds_read_b128 v[216:219], v174 offset:55296
	ds_read_b128 v[220:223], v174 offset:56320
	global_load_lds_dwordx4 v[224:225], off
	s_add_i32 m0, s62, 0x2000
	s_add_u32 s62, s78, 0x40080
	v_lshl_add_u64 v[224:225], v[226:227], 0, s[44:45]
	s_addc_u32 s63, s79, 0
	s_add_i32 s64, s71, s21
	global_load_lds_dwordx4 v[224:225], off
	v_lshl_add_u64 v[224:225], s[62:63], 0, v[0:1]
	s_mov_b32 m0, s64
	s_nop 0
	global_load_lds_dwordx4 v[224:225], off
	v_lshl_add_u64 v[224:225], s[62:63], 0, v[150:151]
	s_add_i32 m0, s64, 0x2000
	s_nop 0
	global_load_lds_dwordx4 v[224:225], off
	v_lshl_add_u64 v[224:225], v[228:229], 0, s[44:45]
	s_mov_b32 m0, s35
	s_nop 0
	global_load_lds_dwordx4 v[224:225], off
	v_lshl_add_u64 v[224:225], v[230:231], 0, s[44:45]
	s_mov_b32 m0, s36
	s_nop 0
	global_load_lds_dwordx4 v[224:225], off
	s_waitcnt vmcnt(8)
	s_waitcnt lgkmcnt(0)
	s_barrier
	s_setprio 1
	s_waitcnt lgkmcnt(0)
	v_mfma_f32_16x16x32_bf16 v[62:65], v[130:133], v[192:195], v[62:65]
	v_mfma_f32_16x16x32_bf16 v[58:61], v[138:141], v[192:195], v[58:61]
	v_mfma_f32_16x16x32_bf16 v[46:49], v[130:133], v[200:203], v[46:49]
	v_mfma_f32_16x16x32_bf16 v[42:45], v[138:141], v[200:203], v[42:45]
	v_mfma_f32_16x16x32_bf16 v[30:33], v[130:133], v[208:211], v[30:33]
	v_mfma_f32_16x16x32_bf16 v[26:29], v[138:141], v[208:211], v[26:29]
	v_mfma_f32_16x16x32_bf16 v[14:17], v[130:133], v[216:219], v[14:17]
	v_mfma_f32_16x16x32_bf16 v[10:13], v[138:141], v[216:219], v[10:13]
	v_mfma_f32_16x16x32_bf16 v[62:65], v[134:137], v[196:199], v[62:65]
	v_mfma_f32_16x16x32_bf16 v[58:61], v[142:145], v[196:199], v[58:61]
	v_mfma_f32_16x16x32_bf16 v[46:49], v[134:137], v[204:207], v[46:49]
	v_mfma_f32_16x16x32_bf16 v[42:45], v[142:145], v[204:207], v[42:45]
	v_mfma_f32_16x16x32_bf16 v[30:33], v[134:137], v[212:215], v[30:33]
	v_mfma_f32_16x16x32_bf16 v[26:29], v[142:145], v[212:215], v[26:29]
	v_mfma_f32_16x16x32_bf16 v[14:17], v[134:137], v[220:223], v[14:17]
	v_mfma_f32_16x16x32_bf16 v[10:13], v[142:145], v[220:223], v[10:13]
	s_setprio 0
	s_setprio 1
	v_mfma_f32_16x16x32_bf16 v[54:57], v[162:165], v[192:195], v[54:57]
	v_mfma_f32_16x16x32_bf16 v[50:53], v[184:187], v[192:195], v[50:53]
	v_mfma_f32_16x16x32_bf16 v[38:41], v[162:165], v[200:203], v[38:41]
	v_mfma_f32_16x16x32_bf16 v[34:37], v[184:187], v[200:203], v[34:37]
	v_mfma_f32_16x16x32_bf16 v[22:25], v[162:165], v[208:211], v[22:25]
	v_mfma_f32_16x16x32_bf16 v[18:21], v[184:187], v[208:211], v[18:21]
	v_mfma_f32_16x16x32_bf16 v[6:9], v[162:165], v[216:219], v[6:9]
	v_mfma_f32_16x16x32_bf16 v[2:5], v[184:187], v[216:219], v[2:5]
	v_mfma_f32_16x16x32_bf16 v[54:57], v[166:169], v[196:199], v[54:57]
	v_mfma_f32_16x16x32_bf16 v[50:53], v[188:191], v[196:199], v[50:53]
	v_mfma_f32_16x16x32_bf16 v[38:41], v[166:169], v[204:207], v[38:41]
	v_mfma_f32_16x16x32_bf16 v[34:37], v[188:191], v[204:207], v[34:37]
	v_mfma_f32_16x16x32_bf16 v[22:25], v[166:169], v[212:215], v[22:25]
	v_mfma_f32_16x16x32_bf16 v[18:21], v[188:191], v[212:215], v[18:21]
	v_mfma_f32_16x16x32_bf16 v[6:9], v[166:169], v[220:223], v[6:9]
	v_mfma_f32_16x16x32_bf16 v[2:5], v[188:191], v[220:223], v[2:5]
	s_setprio 0
	s_barrier
	s_add_i32 s61, s61, 2
	s_add_u32 s6, s6, 0x100
	s_addc_u32 s7, s7, 0
	s_add_u32 s59, s59, 0x100
	s_addc_u32 s60, s60, 0
	s_cmp_gt_u32 s61, 13
	s_cbranch_scc0 .LBB0_92
	s_and_b64 vcc, exec, s[66:67]
	s_cbranch_vccz .LBB0_95
	s_barrier

.LBB0_280:
	s_waitcnt lgkmcnt(7)
	v_mfma_f32_32x32x16_bf16 v[144:159], v[220:223], v[184:187], v[80:95]
	v_add_f32_e32 v2, v112, v113
	v_add_f32_e32 v2, v114, v2
	v_add_f32_e32 v2, v115, v2
	s_lshl_b32 s72, s72, 1
	v_add_f32_e32 v2, v116, v2
	v_add_u32_e32 v0, s72, v245
	v_add_f32_e32 v2, v117, v2
	v_cvt_pk_bf16_f32 v188, v112, v113
	v_cvt_pk_bf16_f32 v189, v114, v115
	s_waitcnt lgkmcnt(6)
	v_mfma_f32_32x32x16_bf16 v[128:143], v[212:215], v[184:187], v[80:95]
	v_add_f32_e32 v2, v118, v2
	v_add_f32_e32 v2, v119, v2
	v_add_f32_e32 v2, v120, v2
	v_add_f32_e32 v2, v121, v2
	v_cvt_pk_bf16_f32 v190, v116, v117
	v_cvt_pk_bf16_f32 v191, v118, v119
	s_waitcnt lgkmcnt(5)
	v_mfma_f32_32x32x16_bf16 v[144:159], v[216:219], v[176:179], v[144:159]
	v_add_f32_e32 v2, v122, v2
	v_add_f32_e32 v2, v123, v2
	v_add_f32_e32 v2, v124, v2
	v_add_f32_e32 v2, v125, v2
	v_cvt_pk_bf16_f32 v180, v120, v121
	v_cvt_pk_bf16_f32 v181, v122, v123
	s_waitcnt lgkmcnt(4)
	v_mfma_f32_32x32x16_bf16 v[128:143], v[204:207], v[176:179], v[128:143]
	v_add_f32_e32 v2, v126, v2
	v_add_f32_e32 v2, v127, v2
	v_add_f32_e32 v2, v96, v2
	v_add_f32_e32 v2, v97, v2
	v_cvt_pk_bf16_f32 v182, v124, v125
	v_cvt_pk_bf16_f32 v183, v126, v127
	s_waitcnt lgkmcnt(3)
	v_mfma_f32_32x32x16_bf16 v[144:159], v[208:211], v[172:175], v[144:159]
	v_add_f32_e32 v2, v98, v2
	v_add_f32_e32 v2, v99, v2
	v_add_f32_e32 v2, v100, v2
	v_add_f32_e32 v2, v101, v2
	v_cvt_pk_bf16_f32 v168, v96, v97
	v_cvt_pk_bf16_f32 v169, v98, v99
	s_waitcnt lgkmcnt(2)
	v_mfma_f32_32x32x16_bf16 v[128:143], v[200:203], v[172:175], v[128:143]
	v_add_f32_e32 v2, v102, v2
	v_add_f32_e32 v2, v103, v2
	v_add_f32_e32 v2, v104, v2
	v_add_f32_e32 v6, v105, v2
	v_cvt_pk_bf16_f32 v170, v100, v101
	v_cvt_pk_bf16_f32 v171, v102, v103
	ds_read_b64_tr_b16 v[2:3], v0 offset:24576
	ds_read_b64_tr_b16 v[4:5], v0 offset:25088
	s_waitcnt lgkmcnt(3)
	v_mfma_f32_32x32x16_bf16 v[144:159], v[196:199], v[164:167], v[144:159]
	v_add_f32_e32 v6, v106, v6
	v_add_f32_e32 v6, v107, v6
	v_add_f32_e32 v6, v108, v6
	v_add_f32_e32 v10, v109, v6
	v_cvt_pk_bf16_f32 v160, v104, v105
	v_cvt_pk_bf16_f32 v161, v106, v107
	ds_read_b64_tr_b16 v[6:7], v0 offset:28672
	ds_read_b64_tr_b16 v[8:9], v0 offset:29184
	s_waitcnt lgkmcnt(4)
	v_mfma_f32_32x32x16_bf16 v[128:143], v[192:195], v[164:167], v[128:143]
	ds_read_b64_tr_b16 v[100:101], v0 offset:32768
	ds_read_b64_tr_b16 v[102:103], v0 offset:33280
	ds_read_b64_tr_b16 v[104:105], v0 offset:36864
	ds_read_b64_tr_b16 v[106:107], v0 offset:37376
	ds_read_b64_tr_b16 v[112:113], v0 offset:25600
	ds_read_b64_tr_b16 v[114:115], v0 offset:26112
	ds_read_b64_tr_b16 v[116:117], v0 offset:29696
	ds_read_b64_tr_b16 v[118:119], v0 offset:30208
	v_add_f32_e32 v10, v110, v10
	v_add_f32_e32 v10, v111, v10
	v_add_f32_e32 v12, 0, v10
	v_cvt_pk_bf16_f32 v162, v108, v109
	v_cvt_pk_bf16_f32 v163, v110, v111
	v_lshl_add_u64 v[14:15], v[234:235], 0, s[6:7]
	v_lshl_add_u64 v[10:11], v[14:15], 0, s[56:57]
	s_add_i32 s72, s78, s64
	v_lshl_add_u64 v[208:209], v[236:237], 0, s[6:7]
	s_mov_b32 s73, m0
	s_mov_b32 m0, s72
	s_nop 0
	global_load_lds_dwordx4 v[10:11], off
	s_mov_b32 m0, s73
	v_lshl_add_u64 v[10:11], v[208:209], 0, s[48:49]
	s_lshl_b32 s72, s76, 1
	v_lshl_add_u64 v[210:211], v[238:239], 0, s[6:7]
	s_add_i32 s72, s72, s63
	s_mov_b32 s73, m0
	s_mov_b32 m0, s72
	s_nop 0
	global_load_lds_dwordx4 v[10:11], off
	s_mov_b32 m0, s73
	v_lshl_add_u64 v[10:11], v[210:211], 0, s[48:49]
	s_addk_i32 s72, 0x2000
	s_mov_b32 s73, m0
	s_mov_b32 m0, s72
	s_nop 0
	global_load_lds_dwordx4 v[10:11], off
	s_mov_b32 m0, s73
	v_max_f32_e32 v10, v145, v145
	v_max_f32_e32 v11, v144, v144
	v_max_f32_e32 v10, v11, v10
	v_max3_f32 v11, v146, v147, v129
	v_max3_f32 v10, v10, v128, v130
	v_max3_f32 v10, v10, v131, v148
	v_max3_f32 v11, v11, v150, v151
	v_max3_f32 v10, v10, v149, v132
	v_max3_f32 v11, v11, v134, v135
	v_max3_f32 v10, v10, v133, v152
	v_max3_f32 v11, v11, v154, v155
	v_max3_f32 v10, v10, v153, v136
	v_max3_f32 v11, v11, v138, v139
	v_max3_f32 v10, v10, v137, v156
	v_max3_f32 v11, v11, v158, v159
	v_max3_f32 v10, v10, v157, v140
	v_max3_f32 v11, v11, v142, v143
	v_max3_f32 v10, v10, v141, v11
	v_mov_b32_e32 v11, v10
	s_nop 1
	v_permlane32_swap_b32_e32 v10, v11
	v_max_f32_e32 v11, v11, v11
	v_max_f32_e32 v10, v10, v10
	v_max_f32_e32 v10, v10, v11
	v_cmp_lt_f32_e32 vcc, s96, v10
	s_cmp_lg_u64 vcc, 0
	v_add_f32_e32 v212, v231, v12
	s_cselect_b64 s[72:73], -1, 0
	s_cbranch_vccnz .LBB0_288
.LBB0_281:
	s_waitcnt lgkmcnt(10)
	v_mfma_f32_32x32x16_bf16 v[64:79], v[188:191], v[2:5], v[64:79]
	v_exp_f32_e32 v144, v144
	v_exp_f32_e32 v145, v145
	s_waitcnt lgkmcnt(8)
	v_mfma_f32_32x32x16_bf16 v[48:63], v[188:191], v[6:9], v[48:63]
	v_exp_f32_e32 v146, v146
	v_exp_f32_e32 v147, v147
	v_add_u32_e32 v108, s76, v225
	ds_read_b128 v[96:99], v108
	ds_read_b128 v[10:13], v108 offset:512
	s_waitcnt lgkmcnt(8)
	v_mfma_f32_32x32x16_bf16 v[32:47], v[188:191], v[100:103], v[32:47]
	v_exp_f32_e32 v148, v148
	v_exp_f32_e32 v149, v149
	ds_read_b64_tr_b16 v[100:101], v0 offset:33792
	ds_read_b64_tr_b16 v[102:103], v0 offset:34304
	s_waitcnt lgkmcnt(8)
	v_mfma_f32_32x32x16_bf16 v[16:31], v[188:191], v[104:107], v[16:31]
	v_exp_f32_e32 v150, v150
	v_exp_f32_e32 v151, v151
	ds_read_b128 v[204:207], v108 offset:2048
	ds_read_b128 v[192:195], v108 offset:2560
	ds_read_b64_tr_b16 v[104:105], v0 offset:37888
	ds_read_b64_tr_b16 v[106:107], v0 offset:38400
	s_waitcnt lgkmcnt(10)
	v_mfma_f32_32x32x16_bf16 v[64:79], v[180:183], v[112:115], v[64:79]
	v_exp_f32_e32 v152, v152
	v_exp_f32_e32 v153, v153
	ds_read_b64_tr_b16 v[112:113], v0 offset:26624
	ds_read_b64_tr_b16 v[114:115], v0 offset:27136
	s_waitcnt lgkmcnt(10)
	v_mfma_f32_32x32x16_bf16 v[48:63], v[180:183], v[116:119], v[48:63]
	v_exp_f32_e32 v154, v154
	v_exp_f32_e32 v155, v155
	ds_read_b128 v[200:203], v108 offset:4096
	ds_read_b128 v[6:9], v108 offset:4608
	ds_read_b64_tr_b16 v[116:117], v0 offset:30720
	ds_read_b64_tr_b16 v[118:119], v0 offset:31232
	s_waitcnt lgkmcnt(10)
	v_mfma_f32_32x32x16_bf16 v[32:47], v[180:183], v[100:103], v[32:47]
	v_exp_f32_e32 v156, v156
	v_exp_f32_e32 v157, v157
	ds_read_b64_tr_b16 v[100:101], v0 offset:34816
	ds_read_b64_tr_b16 v[102:103], v0 offset:35328
	s_waitcnt lgkmcnt(8)
	v_mfma_f32_32x32x16_bf16 v[16:31], v[180:183], v[104:107], v[16:31]
	v_exp_f32_e32 v158, v158
	v_exp_f32_e32 v159, v159
	ds_read_b128 v[196:199], v108 offset:6144
	ds_read_b128 v[2:5], v108 offset:6656
	ds_read_b64_tr_b16 v[104:105], v0 offset:38912
	ds_read_b64_tr_b16 v[106:107], v0 offset:39424
	s_waitcnt lgkmcnt(10)
	v_mfma_f32_32x32x16_bf16 v[64:79], v[168:171], v[112:115], v[64:79]
	v_exp_f32_e32 v128, v128
	v_exp_f32_e32 v129, v129
	ds_read_b64_tr_b16 v[112:113], v0 offset:27648
	ds_read_b64_tr_b16 v[114:115], v0 offset:28160
	s_waitcnt lgkmcnt(8)
	v_mfma_f32_32x32x16_bf16 v[48:63], v[168:171], v[116:119], v[48:63]
	v_exp_f32_e32 v130, v130
	v_exp_f32_e32 v131, v131
	ds_read_b64_tr_b16 v[116:117], v0 offset:31744
	ds_read_b64_tr_b16 v[118:119], v0 offset:32256
	s_waitcnt lgkmcnt(8)
	v_mfma_f32_32x32x16_bf16 v[32:47], v[168:171], v[100:103], v[32:47]
	v_exp_f32_e32 v132, v132
	v_exp_f32_e32 v133, v133
	ds_read_b64_tr_b16 v[100:101], v0 offset:35840
	ds_read_b64_tr_b16 v[102:103], v0 offset:36352
	s_waitcnt lgkmcnt(6)
	v_mfma_f32_32x32x16_bf16 v[16:31], v[168:171], v[104:107], v[16:31]
	v_exp_f32_e32 v134, v134
	v_exp_f32_e32 v135, v135
	ds_read_b64_tr_b16 v[104:105], v0 offset:39936
	ds_read_b64_tr_b16 v[106:107], v0 offset:40448
	s_waitcnt lgkmcnt(6)
	v_mfma_f32_32x32x16_bf16 v[64:79], v[160:163], v[112:115], v[64:79]
	v_exp_f32_e32 v136, v136
	v_exp_f32_e32 v137, v137
	s_waitcnt lgkmcnt(4)
	v_mfma_f32_32x32x16_bf16 v[48:63], v[160:163], v[116:119], v[48:63]
	v_exp_f32_e32 v138, v138
	v_exp_f32_e32 v139, v139
	s_waitcnt lgkmcnt(2)
	v_mfma_f32_32x32x16_bf16 v[32:47], v[160:163], v[100:103], v[32:47]
	v_exp_f32_e32 v140, v140
	v_exp_f32_e32 v141, v141
	s_waitcnt lgkmcnt(0)
	v_mfma_f32_32x32x16_bf16 v[16:31], v[160:163], v[104:107], v[16:31]
	v_exp_f32_e32 v142, v142
	v_exp_f32_e32 v143, v143
	s_waitcnt vmcnt(3) lgkmcnt(0)
	s_barrier
	s_andn2_b64 vcc, exec, s[72:73]
	v_add_u32_e32 v0, s62, v230
	s_cbranch_vccnz .LBB0_283
	s_waitcnt lgkmcnt(0)
	ds_read_b128 v[100:103], v0 offset:96
	ds_read_b128 v[104:107], v0 offset:64
	ds_read_b128 v[108:111], v0 offset:32
	ds_read_b128 v[112:115], v0
	s_waitcnt lgkmcnt(3)
	v_pk_mul_f32 v[76:77], v[76:77], v[100:101]
	s_waitcnt lgkmcnt(2)
	v_pk_mul_f32 v[72:73], v[72:73], v[104:105]
	s_waitcnt lgkmcnt(1)
	v_pk_mul_f32 v[68:69], v[68:69], v[108:109]
	v_pk_mul_f32 v[78:79], v[78:79], v[102:103]
	v_pk_mul_f32 v[74:75], v[74:75], v[106:107]
	v_pk_mul_f32 v[70:71], v[70:71], v[110:111]
	s_waitcnt lgkmcnt(0)
	v_pk_mul_f32 v[66:67], v[66:67], v[114:115]
	v_pk_mul_f32 v[64:65], v[64:65], v[112:113]
	v_pk_mul_f32 v[60:61], v[60:61], v[100:101]
	v_pk_mul_f32 v[56:57], v[56:57], v[104:105]
	v_pk_mul_f32 v[52:53], v[52:53], v[108:109]
	v_pk_mul_f32 v[62:63], v[62:63], v[102:103]
	v_pk_mul_f32 v[58:59], v[58:59], v[106:107]
	v_pk_mul_f32 v[54:55], v[54:55], v[110:111]
	v_pk_mul_f32 v[50:51], v[50:51], v[114:115]
	v_pk_mul_f32 v[48:49], v[48:49], v[112:113]
	v_pk_mul_f32 v[44:45], v[44:45], v[100:101]
	v_pk_mul_f32 v[40:41], v[40:41], v[104:105]
	v_pk_mul_f32 v[36:37], v[36:37], v[108:109]
	v_pk_mul_f32 v[46:47], v[46:47], v[102:103]
	v_pk_mul_f32 v[42:43], v[42:43], v[106:107]
	v_pk_mul_f32 v[38:39], v[38:39], v[110:111]
	v_pk_mul_f32 v[34:35], v[34:35], v[114:115]
	v_pk_mul_f32 v[32:33], v[32:33], v[112:113]
	v_pk_mul_f32 v[28:29], v[28:29], v[100:101]
	v_pk_mul_f32 v[24:25], v[24:25], v[104:105]
	v_pk_mul_f32 v[20:21], v[20:21], v[108:109]
	v_pk_mul_f32 v[30:31], v[30:31], v[102:103]
	v_pk_mul_f32 v[26:27], v[26:27], v[106:107]
	v_pk_mul_f32 v[22:23], v[22:23], v[110:111]
	v_pk_mul_f32 v[18:19], v[18:19], v[114:115]
	v_pk_mul_f32 v[16:17], v[16:17], v[112:113]
.LBB0_283:
	s_add_i32 s72, s76, 0x2000
	s_cmpk_lg_i32 s76, 0x4000
	s_cselect_b32 s87, s72, 0
	v_mfma_f32_32x32x16_bf16 v[112:127], v[96:99], v[184:187], v[80:95]
	v_add_f32_e32 v100, v144, v145
	v_add_f32_e32 v100, v146, v100
	v_add_f32_e32 v100, v147, v100
	s_lshl_b32 s72, s78, 1
	v_add_f32_e32 v100, v148, v100
	v_add_u32_e32 v233, s72, v245
	v_add_f32_e32 v96, v149, v100
	v_cvt_pk_bf16_f32 v188, v144, v145
	v_cvt_pk_bf16_f32 v189, v146, v147
	s_nop 0
	v_add_f32_e32 v96, v150, v96
	v_add_f32_e32 v96, v151, v96
	v_add_f32_e32 v96, v152, v96
	v_add_f32_e32 v144, v153, v96
	v_mfma_f32_32x32x16_bf16 v[96:111], v[10:13], v[184:187], v[80:95]
	v_cvt_pk_bf16_f32 v190, v148, v149
	v_cvt_pk_bf16_f32 v191, v150, v151
	v_mfma_f32_32x32x16_bf16 v[112:127], v[204:207], v[176:179], v[112:127]
	v_add_f32_e32 v10, v154, v144
	v_add_f32_e32 v10, v155, v10
	v_add_f32_e32 v10, v156, v10
	v_add_f32_e32 v10, v157, v10
	v_cvt_pk_bf16_f32 v180, v152, v153
	v_cvt_pk_bf16_f32 v181, v154, v155
	v_mfma_f32_32x32x16_bf16 v[96:111], v[192:195], v[176:179], v[96:111]
	v_add_f32_e32 v10, v158, v10
	v_add_f32_e32 v10, v159, v10
	v_add_f32_e32 v10, v128, v10
	v_add_f32_e32 v10, v129, v10
	v_cvt_pk_bf16_f32 v182, v156, v157
	v_cvt_pk_bf16_f32 v183, v158, v159
	v_mfma_f32_32x32x16_bf16 v[112:127], v[200:203], v[172:175], v[112:127]
	v_add_f32_e32 v10, v130, v10
	v_add_f32_e32 v10, v131, v10
	v_add_f32_e32 v10, v132, v10
	v_add_f32_e32 v10, v133, v10
	v_cvt_pk_bf16_f32 v168, v128, v129
	v_cvt_pk_bf16_f32 v169, v130, v131
	v_mfma_f32_32x32x16_bf16 v[96:111], v[6:9], v[172:175], v[96:111]
	v_add_f32_e32 v6, v134, v10
	v_add_f32_e32 v6, v135, v6
	v_add_f32_e32 v6, v136, v6
	v_add_f32_e32 v10, v137, v6
	v_cvt_pk_bf16_f32 v170, v132, v133
	v_cvt_pk_bf16_f32 v171, v134, v135
	ds_read_b64_tr_b16 v[6:7], v233 offset:24576
	ds_read_b64_tr_b16 v[8:9], v233 offset:25088
	v_mfma_f32_32x32x16_bf16 v[112:127], v[196:199], v[164:167], v[112:127]
	v_add_f32_e32 v10, v138, v10
	v_add_f32_e32 v10, v139, v10
	v_add_f32_e32 v10, v140, v10
	v_add_f32_e32 v128, v141, v10
	v_cvt_pk_bf16_f32 v160, v136, v137
	v_cvt_pk_bf16_f32 v161, v138, v139
	ds_read_b64_tr_b16 v[10:11], v233 offset:28672
	ds_read_b64_tr_b16 v[12:13], v233 offset:29184
	v_mfma_f32_32x32x16_bf16 v[96:111], v[2:5], v[164:167], v[96:111]
	ds_read_b64_tr_b16 v[144:145], v233 offset:32768
	ds_read_b64_tr_b16 v[146:147], v233 offset:33280
	ds_read_b64_tr_b16 v[148:149], v233 offset:36864
	ds_read_b64_tr_b16 v[150:151], v233 offset:37376
	ds_read_b64_tr_b16 v[152:153], v233 offset:25600
	ds_read_b64_tr_b16 v[154:155], v233 offset:26112
	ds_read_b64_tr_b16 v[156:157], v233 offset:29696
	ds_read_b64_tr_b16 v[158:159], v233 offset:30208
	v_add_f32_e32 v2, v142, v128
	v_add_f32_e32 v2, v143, v2
	v_add_f32_e32 v4, 0, v2
	v_cvt_pk_bf16_f32 v162, v140, v141
	v_cvt_pk_bf16_f32 v163, v142, v143
	v_lshl_add_u64 v[2:3], v[14:15], 0, s[52:53]
	s_add_i32 s72, s76, s64
	s_mov_b32 s73, m0
	s_mov_b32 m0, s72
	s_nop 0
	global_load_lds_dwordx4 v[2:3], off
	s_mov_b32 m0, s73
	v_lshl_add_u64 v[2:3], v[208:209], 0, s[50:51]
	s_lshl_b32 s72, s87, 1
	s_add_i32 s72, s72, s63
	s_mov_b32 s73, m0
	s_mov_b32 m0, s72
	s_nop 0
	global_load_lds_dwordx4 v[2:3], off
	s_mov_b32 m0, s73
	v_lshl_add_u64 v[2:3], v[210:211], 0, s[50:51]
	s_addk_i32 s72, 0x2000
	s_mov_b32 s73, m0
	s_mov_b32 m0, s72
	s_nop 0
	global_load_lds_dwordx4 v[2:3], off
	s_mov_b32 m0, s73
	v_max_f32_e32 v2, v113, v113
	v_max_f32_e32 v3, v112, v112
	v_max_f32_e32 v2, v3, v2
	v_max3_f32 v3, v114, v115, v97
	v_max3_f32 v2, v2, v96, v98
	v_max3_f32 v2, v2, v99, v116
	v_max3_f32 v3, v3, v118, v119
	v_max3_f32 v2, v2, v117, v100
	v_max3_f32 v3, v3, v102, v103
	v_max3_f32 v2, v2, v101, v120
	v_max3_f32 v3, v3, v122, v123
	v_max3_f32 v2, v2, v121, v104
	v_max3_f32 v3, v3, v106, v107
	v_max3_f32 v2, v2, v105, v124
	v_max3_f32 v3, v3, v126, v127
	v_max3_f32 v2, v2, v125, v108
	v_max3_f32 v3, v3, v110, v111
	v_max3_f32 v2, v2, v109, v3
	v_mov_b32_e32 v3, v2
	s_nop 1
	v_permlane32_swap_b32_e32 v2, v3
	v_max_f32_e32 v3, v3, v3
	v_max_f32_e32 v2, v2, v2
	v_max_f32_e32 v2, v2, v3
	v_cmp_lt_f32_e32 vcc, s96, v2
	s_cmp_lg_u64 vcc, 0
	v_add_f32_e32 v231, v212, v4
	s_cselect_b64 s[72:73], -1, 0
	s_cbranch_vccnz .LBB0_291
.LBB0_284:
	s_waitcnt lgkmcnt(10)
	v_mfma_f32_32x32x16_bf16 v[64:79], v[188:191], v[6:9], v[64:79]
	v_exp_f32_e32 v112, v112
	v_exp_f32_e32 v113, v113
	s_waitcnt lgkmcnt(8)
	v_mfma_f32_32x32x16_bf16 v[48:63], v[188:191], v[10:13], v[48:63]
	v_exp_f32_e32 v114, v114
	v_exp_f32_e32 v115, v115
	v_add_u32_e32 v10, s87, v225
	ds_read_b128 v[220:223], v10
	ds_read_b128 v[212:215], v10 offset:512
	s_waitcnt lgkmcnt(8)
	v_mfma_f32_32x32x16_bf16 v[32:47], v[188:191], v[144:147], v[32:47]
	v_exp_f32_e32 v116, v116
	v_exp_f32_e32 v117, v117
	ds_read_b64_tr_b16 v[144:145], v233 offset:33792
	ds_read_b64_tr_b16 v[146:147], v233 offset:34304
	s_waitcnt lgkmcnt(8)
	v_mfma_f32_32x32x16_bf16 v[16:31], v[188:191], v[148:151], v[16:31]
	v_exp_f32_e32 v118, v118
	v_exp_f32_e32 v119, v119
	ds_read_b128 v[216:219], v10 offset:2048
	ds_read_b128 v[204:207], v10 offset:2560
	ds_read_b64_tr_b16 v[148:149], v233 offset:37888
	ds_read_b64_tr_b16 v[150:151], v233 offset:38400
	s_waitcnt lgkmcnt(10)
	v_mfma_f32_32x32x16_bf16 v[64:79], v[180:183], v[152:155], v[64:79]
	v_exp_f32_e32 v120, v120
	v_exp_f32_e32 v121, v121
	ds_read_b64_tr_b16 v[152:153], v233 offset:26624
	ds_read_b64_tr_b16 v[154:155], v233 offset:27136
	s_waitcnt lgkmcnt(10)
	v_mfma_f32_32x32x16_bf16 v[48:63], v[180:183], v[156:159], v[48:63]
	v_exp_f32_e32 v122, v122
	v_exp_f32_e32 v123, v123
	ds_read_b128 v[208:211], v10 offset:4096
	ds_read_b128 v[200:203], v10 offset:4608
	ds_read_b64_tr_b16 v[156:157], v233 offset:30720
	ds_read_b64_tr_b16 v[158:159], v233 offset:31232
	s_waitcnt lgkmcnt(10)
	v_mfma_f32_32x32x16_bf16 v[32:47], v[180:183], v[144:147], v[32:47]
	v_exp_f32_e32 v124, v124
	v_exp_f32_e32 v125, v125
	ds_read_b64_tr_b16 v[144:145], v233 offset:34816
	ds_read_b64_tr_b16 v[146:147], v233 offset:35328
	s_waitcnt lgkmcnt(8)
	v_mfma_f32_32x32x16_bf16 v[16:31], v[180:183], v[148:151], v[16:31]
	v_exp_f32_e32 v126, v126
	v_exp_f32_e32 v127, v127
	ds_read_b128 v[196:199], v10 offset:6144
	ds_read_b128 v[192:195], v10 offset:6656
	ds_read_b64_tr_b16 v[148:149], v233 offset:38912
	ds_read_b64_tr_b16 v[150:151], v233 offset:39424
	s_waitcnt lgkmcnt(10)
	v_mfma_f32_32x32x16_bf16 v[64:79], v[168:171], v[152:155], v[64:79]
	v_exp_f32_e32 v96, v96
	v_exp_f32_e32 v97, v97
	ds_read_b64_tr_b16 v[152:153], v233 offset:27648
	ds_read_b64_tr_b16 v[154:155], v233 offset:28160
	s_waitcnt lgkmcnt(8)
	v_mfma_f32_32x32x16_bf16 v[48:63], v[168:171], v[156:159], v[48:63]
	v_exp_f32_e32 v98, v98
	v_exp_f32_e32 v99, v99
	ds_read_b64_tr_b16 v[156:157], v233 offset:31744
	ds_read_b64_tr_b16 v[158:159], v233 offset:32256
	s_waitcnt lgkmcnt(8)
	v_mfma_f32_32x32x16_bf16 v[32:47], v[168:171], v[144:147], v[32:47]
	v_exp_f32_e32 v100, v100
	v_exp_f32_e32 v101, v101
	ds_read_b64_tr_b16 v[144:145], v233 offset:35840
	ds_read_b64_tr_b16 v[146:147], v233 offset:36352
	s_waitcnt lgkmcnt(6)
	v_mfma_f32_32x32x16_bf16 v[16:31], v[168:171], v[148:151], v[16:31]
	v_exp_f32_e32 v102, v102
	v_exp_f32_e32 v103, v103
	ds_read_b64_tr_b16 v[148:149], v233 offset:39936
	ds_read_b64_tr_b16 v[150:151], v233 offset:40448
	s_waitcnt lgkmcnt(6)
	v_mfma_f32_32x32x16_bf16 v[64:79], v[160:163], v[152:155], v[64:79]
	v_exp_f32_e32 v104, v104
	v_exp_f32_e32 v105, v105
	s_waitcnt lgkmcnt(4)
	v_mfma_f32_32x32x16_bf16 v[48:63], v[160:163], v[156:159], v[48:63]
	v_exp_f32_e32 v106, v106
	v_exp_f32_e32 v107, v107
	s_waitcnt lgkmcnt(2)
	v_mfma_f32_32x32x16_bf16 v[32:47], v[160:163], v[144:147], v[32:47]
	v_exp_f32_e32 v108, v108
	v_exp_f32_e32 v109, v109
	s_waitcnt lgkmcnt(0)
	v_mfma_f32_32x32x16_bf16 v[16:31], v[160:163], v[148:151], v[16:31]
	v_exp_f32_e32 v110, v110
	v_exp_f32_e32 v111, v111
	s_waitcnt vmcnt(3) lgkmcnt(0)
	s_barrier
	s_andn2_b64 vcc, exec, s[72:73]
	s_cbranch_vccnz .LBB0_286
	s_waitcnt lgkmcnt(0)
	ds_read_b128 v[2:5], v0 offset:96
	ds_read_b128 v[6:9], v0 offset:64
	ds_read_b128 v[10:13], v0 offset:32
	ds_read_b128 v[128:131], v0
	s_waitcnt lgkmcnt(3)
	v_pk_mul_f32 v[76:77], v[76:77], v[2:3]
	s_waitcnt lgkmcnt(2)
	v_pk_mul_f32 v[72:73], v[72:73], v[6:7]
	s_waitcnt lgkmcnt(1)
	v_pk_mul_f32 v[68:69], v[68:69], v[10:11]
	v_pk_mul_f32 v[78:79], v[78:79], v[4:5]
	v_pk_mul_f32 v[74:75], v[74:75], v[8:9]
	v_pk_mul_f32 v[70:71], v[70:71], v[12:13]
	s_waitcnt lgkmcnt(0)
	v_pk_mul_f32 v[66:67], v[66:67], v[130:131]
	v_pk_mul_f32 v[64:65], v[64:65], v[128:129]
	v_pk_mul_f32 v[60:61], v[60:61], v[2:3]
	v_pk_mul_f32 v[56:57], v[56:57], v[6:7]
	v_pk_mul_f32 v[52:53], v[52:53], v[10:11]
	v_pk_mul_f32 v[62:63], v[62:63], v[4:5]
	v_pk_mul_f32 v[58:59], v[58:59], v[8:9]
	v_pk_mul_f32 v[54:55], v[54:55], v[12:13]
	v_pk_mul_f32 v[50:51], v[50:51], v[130:131]
	v_pk_mul_f32 v[48:49], v[48:49], v[128:129]
	v_pk_mul_f32 v[44:45], v[44:45], v[2:3]
	v_pk_mul_f32 v[40:41], v[40:41], v[6:7]
	v_pk_mul_f32 v[36:37], v[36:37], v[10:11]
	v_pk_mul_f32 v[46:47], v[46:47], v[4:5]
	v_pk_mul_f32 v[42:43], v[42:43], v[8:9]
	v_pk_mul_f32 v[38:39], v[38:39], v[12:13]
	v_pk_mul_f32 v[34:35], v[34:35], v[130:131]
	v_pk_mul_f32 v[32:33], v[32:33], v[128:129]
	v_pk_mul_f32 v[28:29], v[28:29], v[2:3]
	v_pk_mul_f32 v[24:25], v[24:25], v[6:7]
	v_pk_mul_f32 v[20:21], v[20:21], v[10:11]
	v_pk_mul_f32 v[30:31], v[30:31], v[4:5]
	v_pk_mul_f32 v[26:27], v[26:27], v[8:9]
	v_pk_mul_f32 v[22:23], v[22:23], v[12:13]
	v_pk_mul_f32 v[18:19], v[18:19], v[130:131]
	v_pk_mul_f32 v[16:17], v[16:17], v[128:129]

; #define PG8_STAGE(bufoff, gbase, voff) do { _Pragma("unroll") for (int _i = 0; _i < 2; ++_i) \
;         __builtin_amdgcn_global_load_lds((const unsigned*)((const char*)(gbase) + (voff)[_i]), (PG8_LAS unsigned*)(lds + (bufoff) + ldsw + _i * 8192), 16, 0, 0); } while (0)
; #define PG8_LDA(dst, b, h) do { _Pragma("unroll") for (int m = 0; m < 4; ++m) _Pragma("unroll") for (int k = 0; k < 2; ++k) dst[m][k] = *(const PG8_LAS bf16x8*)(lds + PG8_SA(b, h) + aoff + m * 2048 + k * 1024); } while (0)
; #define PG8_LDB(dst, b, h) do { _Pragma("unroll") for (int n = 0; n < 2; ++n) _Pragma("unroll") for (int k = 0; k < 2; ++k) dst[n][k] = *(const PG8_LAS bf16x8*)(lds + PG8_SB(b, h) + boff + n * 2048 + k * 1024); } while (0)
; #define PG8_MMA(ai, bj, At, Bt) do { __builtin_amdgcn_s_setprio(1); _Pragma("unroll") for (int m = 0; m < 4; ++m) _Pragma("unroll") for (int n = 0; n < 2; ++n) _Pragma("unroll") for (int k = 0; k < 2; ++k) \
;         acc[ai][bj][m][n] = __builtin_amdgcn_mfma_f32_16x16x32_bf16(Bt[n][k], At[m][k], acc[ai][bj][m][n], 0, 0, 0); __builtin_amdgcn_s_setprio(0); } while (0)
; #define PG8_BAR __builtin_amdgcn_s_barrier()
; template <class Epi, class Sched, bool ALIGN_EPI = false, bool SP2 = false>
; __device__ __forceinline__ void gemm_phase(PG8_LAS unsigned char* lds, const Gemm g, const Sched& S, const Epi& E, const int tid_in) {
;     ...
;             PG8_LDB(B0, 0, 0); PG8_LDB(B1, 0, 1); PG8_SCHED; PG8_LDA(At, 0, 0); PG8_STAGE(PG8_SA(1, 1), a1 + hstep, voffA);
;             PG8_WAIT_V(8); PG8_WAIT_L(0); PG8_BAR; PG8_MMA(0, 0, At, B0); PG8_MMA(0, 1, At, B1); PG8_BAR; PG8_SCHED;
;             PG8_LDA(At, 0, 1); PG8_STAGE(PG8_SB(0, 0), b2, voffB); PG8_STAGE(PG8_SB(0, 1), b2 + hstep, voffB); PG8_STAGE(PG8_SA(0, 0), a2, voffA);
;             PG8_WAIT_V(8); PG8_WAIT_L(0); PG8_BAR; PG8_MMA(1, 0, At, B0); PG8_MMA(1, 1, At, B1); PG8_BAR; PG8_SCHED;
;             PG8_LDB(B0, 1, 0); PG8_LDB(B1, 1, 1); PG8_SCHED; PG8_LDA(At, 1, 0); PG8_STAGE(PG8_SA(0, 1), a2 + hstep, voffA);
;             PG8_WAIT_V(8); PG8_WAIT_L(0); PG8_BAR; PG8_MMA(0, 0, At, B0); PG8_MMA(0, 1, At, B1); PG8_BAR; PG8_SCHED;
;             PG8_LDA(At, 1, 1); PG8_STAGE(PG8_SB(1, 0), b3, voffB); PG8_STAGE(PG8_SB(1, 1), b3 + hstep, voffB); PG8_STAGE(PG8_SA(1, 0), a3, voffA);
;             PG8_WAIT_V(8); PG8_WAIT_L(0); PG8_BAR; PG8_MMA(1, 0, At, B0); PG8_MMA(1, 1, At, B1); PG8_BAR; PG8_SCHED;
.LBB0_485:
	s_add_u32 s61, s68, 0xfffc0080
	s_addc_u32 s62, s69, -1
	s_add_i32 s63, 0, 0x10000
	s_cmp_eq_u32 s60, 12
	s_cselect_b32 s73, s15, s62
	s_cselect_b32 s72, s42, s61
	v_add_u32_e32 v140, s63, v143
	s_cselect_b32 s71, s13, s59
	s_cselect_b32 s70, s43, s58
	s_add_i32 s61, 0, 0x14000
	ds_read_b128 v[146:149], v140
	ds_read_b128 v[150:153], v140 offset:1024
	ds_read_b128 v[154:157], v140 offset:2048
	ds_read_b128 v[158:161], v140 offset:3072
	v_add_u32_e32 v140, s61, v143
	ds_read_b128 v[162:165], v140
	ds_read_b128 v[166:169], v140 offset:1024
	ds_read_b128 v[170:173], v140 offset:2048
	ds_read_b128 v[174:177], v140 offset:3072
	v_lshl_add_u64 v[140:141], s[68:69], 0, v[136:137]
	s_add_i32 m0, s17, 0xc000
	ds_read_b128 v[178:181], v145
	ds_read_b128 v[182:185], v145 offset:1024
	ds_read_b128 v[186:189], v145 offset:2048
	ds_read_b128 v[190:193], v145 offset:3072
	ds_read_b128 v[194:197], v145 offset:4096
	ds_read_b128 v[198:201], v145 offset:5120
	ds_read_b128 v[202:205], v145 offset:6144
	ds_read_b128 v[206:209], v145 offset:7168
	global_load_lds_dwordx4 v[140:141], off
	v_lshl_add_u64 v[140:141], s[68:69], 0, v[138:139]
	s_add_i32 m0, s17, 0xe000
	s_nop 0
	global_load_lds_dwordx4 v[140:141], off
	s_waitcnt vmcnt(8)
	s_waitcnt lgkmcnt(0)
	s_barrier
	s_setprio 1
	s_waitcnt lgkmcnt(0)
	v_mfma_f32_16x16x32_bf16 v[126:129], v[146:149], v[178:181], v[126:129]
	v_mfma_f32_16x16x32_bf16 v[122:125], v[154:157], v[178:181], v[122:125]
	v_mfma_f32_16x16x32_bf16 v[118:121], v[146:149], v[186:189], v[118:121]
	v_mfma_f32_16x16x32_bf16 v[110:113], v[154:157], v[186:189], v[110:113]
	v_mfma_f32_16x16x32_bf16 v[102:105], v[146:149], v[194:197], v[102:105]
	v_mfma_f32_16x16x32_bf16 v[94:97], v[154:157], v[194:197], v[94:97]
	v_mfma_f32_16x16x32_bf16 v[86:89], v[146:149], v[202:205], v[86:89]
	v_mfma_f32_16x16x32_bf16 v[78:81], v[154:157], v[202:205], v[78:81]
	v_mfma_f32_16x16x32_bf16 v[126:129], v[150:153], v[182:185], v[126:129]
	v_mfma_f32_16x16x32_bf16 v[122:125], v[158:161], v[182:185], v[122:125]
	v_mfma_f32_16x16x32_bf16 v[118:121], v[150:153], v[190:193], v[118:121]
	v_mfma_f32_16x16x32_bf16 v[110:113], v[158:161], v[190:193], v[110:113]
	v_mfma_f32_16x16x32_bf16 v[102:105], v[150:153], v[198:201], v[102:105]
	v_mfma_f32_16x16x32_bf16 v[94:97], v[158:161], v[198:201], v[94:97]
	v_mfma_f32_16x16x32_bf16 v[86:89], v[150:153], v[206:209], v[86:89]
	v_mfma_f32_16x16x32_bf16 v[78:81], v[158:161], v[206:209], v[78:81]
	s_setprio 0
	s_setprio 1
	v_mfma_f32_16x16x32_bf16 v[114:117], v[162:165], v[178:181], v[114:117]
	v_mfma_f32_16x16x32_bf16 v[106:109], v[170:173], v[178:181], v[106:109]
	v_mfma_f32_16x16x32_bf16 v[98:101], v[162:165], v[186:189], v[98:101]
	v_mfma_f32_16x16x32_bf16 v[90:93], v[170:173], v[186:189], v[90:93]
	v_mfma_f32_16x16x32_bf16 v[82:85], v[162:165], v[194:197], v[82:85]
	v_mfma_f32_16x16x32_bf16 v[74:77], v[170:173], v[194:197], v[74:77]
	v_mfma_f32_16x16x32_bf16 v[70:73], v[162:165], v[202:205], v[70:73]
	v_mfma_f32_16x16x32_bf16 v[66:69], v[170:173], v[202:205], v[66:69]
	v_mfma_f32_16x16x32_bf16 v[114:117], v[166:169], v[182:185], v[114:117]
	v_mfma_f32_16x16x32_bf16 v[106:109], v[174:177], v[182:185], v[106:109]
	v_mfma_f32_16x16x32_bf16 v[98:101], v[166:169], v[190:193], v[98:101]
	v_mfma_f32_16x16x32_bf16 v[90:93], v[174:177], v[190:193], v[90:93]
	v_mfma_f32_16x16x32_bf16 v[82:85], v[166:169], v[198:201], v[82:85]
	v_mfma_f32_16x16x32_bf16 v[74:77], v[174:177], v[198:201], v[74:77]
	v_mfma_f32_16x16x32_bf16 v[70:73], v[166:169], v[206:209], v[70:73]
	v_mfma_f32_16x16x32_bf16 v[66:69], v[174:177], v[206:209], v[66:69]
	s_setprio 0
	s_barrier
	s_add_i32 s62, s63, s26
	v_lshl_add_u64 v[140:141], s[70:71], 0, v[0:1]
	s_mov_b32 m0, s62
	ds_read_b128 v[178:181], v145 offset:16384
	ds_read_b128 v[182:185], v145 offset:17408
	ds_read_b128 v[186:189], v145 offset:18432
	ds_read_b128 v[190:193], v145 offset:19456
	ds_read_b128 v[194:197], v145 offset:20480
	ds_read_b128 v[198:201], v145 offset:21504
	ds_read_b128 v[202:205], v145 offset:22528
	ds_read_b128 v[206:209], v145 offset:23552
	global_load_lds_dwordx4 v[140:141], off
	s_add_i32 m0, s62, 0x2000
	s_add_u32 s62, s70, 0x40000
	v_lshl_add_u64 v[210:211], s[70:71], 0, v[134:135]
	s_addc_u32 s63, s71, 0
	s_add_i32 s61, s61, s26
	global_load_lds_dwordx4 v[210:211], off
	v_lshl_add_u64 v[212:213], s[62:63], 0, v[0:1]
	s_mov_b32 m0, s61
	v_lshl_add_u64 v[214:215], s[72:73], 0, v[132:133]
	global_load_lds_dwordx4 v[212:213], off
	v_lshl_add_u64 v[212:213], s[62:63], 0, v[134:135]
	s_add_i32 m0, s61, 0x2000
	s_nop 0
	global_load_lds_dwordx4 v[212:213], off
	v_lshl_add_u64 v[212:213], s[72:73], 0, v[130:131]
	s_mov_b32 m0, s17
	s_nop 0
	global_load_lds_dwordx4 v[212:213], off
	s_mov_b32 m0, s27
	s_nop 0
	global_load_lds_dwordx4 v[214:215], off
	s_waitcnt vmcnt(8)
	s_waitcnt lgkmcnt(0)
	s_barrier
; #define PG8_STAGE(bufoff, gbase, voff) do { _Pragma("unroll") for (int _i = 0; _i < 2; ++_i) \
;         __builtin_amdgcn_global_load_lds((const unsigned*)((const char*)(gbase) + (voff)[_i]), (PG8_LAS unsigned*)(lds + (bufoff) + ldsw + _i * 8192), 16, 0, 0); } while (0)
; #define PG8_LDA(dst, b, h) do { _Pragma("unroll") for (int m = 0; m < 4; ++m) _Pragma("unroll") for (int k = 0; k < 2; ++k) dst[m][k] = *(const PG8_LAS bf16x8*)(lds + PG8_SA(b, h) + aoff + m * 2048 + k * 1024); } while (0)
; #define PG8_LDB(dst, b, h) do { _Pragma("unroll") for (int n = 0; n < 2; ++n) _Pragma("unroll") for (int k = 0; k < 2; ++k) dst[n][k] = *(const PG8_LAS bf16x8*)(lds + PG8_SB(b, h) + boff + n * 2048 + k * 1024); } while (0)
; #define PG8_MMA(ai, bj, At, Bt) do { __builtin_amdgcn_s_setprio(1); _Pragma("unroll") for (int m = 0; m < 4; ++m) _Pragma("unroll") for (int n = 0; n < 2; ++n) _Pragma("unroll") for (int k = 0; k < 2; ++k) \
;         acc[ai][bj][m][n] = __builtin_amdgcn_mfma_f32_16x16x32_bf16(Bt[n][k], At[m][k], acc[ai][bj][m][n], 0, 0, 0); __builtin_amdgcn_s_setprio(0); } while (0)
; #define PG8_BAR __builtin_amdgcn_s_barrier()
; template <class Epi, class Sched, bool ALIGN_EPI = false, bool SP2 = false>
; __device__ __forceinline__ void gemm_phase(PG8_LAS unsigned char* lds, const Gemm g, const Sched& S, const Epi& E, const int tid_in) {
;     ...
;             PG8_LDB(B0, 0, 0); PG8_LDB(B1, 0, 1); PG8_SCHED; PG8_LDA(At, 0, 0); PG8_STAGE(PG8_SA(1, 1), a1 + hstep, voffA);
;             PG8_WAIT_V(8); PG8_WAIT_L(0); PG8_BAR; PG8_MMA(0, 0, At, B0); PG8_MMA(0, 1, At, B1); PG8_BAR; PG8_SCHED;
;             PG8_LDA(At, 0, 1); PG8_STAGE(PG8_SB(0, 0), b2, voffB); PG8_STAGE(PG8_SB(0, 1), b2 + hstep, voffB); PG8_STAGE(PG8_SA(0, 0), a2, voffA);
;             PG8_WAIT_V(8); PG8_WAIT_L(0); PG8_BAR; PG8_MMA(1, 0, At, B0); PG8_MMA(1, 1, At, B1); PG8_BAR; PG8_SCHED;
;             PG8_LDB(B0, 1, 0); PG8_LDB(B1, 1, 1); PG8_SCHED; PG8_LDA(At, 1, 0); PG8_STAGE(PG8_SA(0, 1), a2 + hstep, voffA);
;             PG8_WAIT_V(8); PG8_WAIT_L(0); PG8_BAR; PG8_MMA(0, 0, At, B0); PG8_MMA(0, 1, At, B1); PG8_BAR; PG8_SCHED;
;             PG8_LDA(At, 1, 1); PG8_STAGE(PG8_SB(1, 0), b3, voffB); PG8_STAGE(PG8_SB(1, 1), b3 + hstep, voffB); PG8_STAGE(PG8_SA(1, 0), a3, voffA);
;             PG8_WAIT_V(8); PG8_WAIT_L(0); PG8_BAR; PG8_MMA(1, 0, At, B0); PG8_MMA(1, 1, At, B1); PG8_BAR; PG8_SCHED;
	s_setprio 1
	s_waitcnt lgkmcnt(0)
	v_mfma_f32_16x16x32_bf16 v[62:65], v[146:149], v[178:181], v[62:65]
	v_mfma_f32_16x16x32_bf16 v[58:61], v[154:157], v[178:181], v[58:61]
	v_mfma_f32_16x16x32_bf16 v[54:57], v[146:149], v[186:189], v[54:57]
	v_mfma_f32_16x16x32_bf16 v[46:49], v[154:157], v[186:189], v[46:49]
	v_mfma_f32_16x16x32_bf16 v[38:41], v[146:149], v[194:197], v[38:41]
	v_mfma_f32_16x16x32_bf16 v[30:33], v[154:157], v[194:197], v[30:33]
	v_mfma_f32_16x16x32_bf16 v[22:25], v[146:149], v[202:205], v[22:25]
	v_mfma_f32_16x16x32_bf16 v[14:17], v[154:157], v[202:205], v[14:17]
	v_mfma_f32_16x16x32_bf16 v[62:65], v[150:153], v[182:185], v[62:65]
	v_mfma_f32_16x16x32_bf16 v[58:61], v[158:161], v[182:185], v[58:61]
	v_mfma_f32_16x16x32_bf16 v[54:57], v[150:153], v[190:193], v[54:57]
	v_mfma_f32_16x16x32_bf16 v[46:49], v[158:161], v[190:193], v[46:49]
	v_mfma_f32_16x16x32_bf16 v[38:41], v[150:153], v[198:201], v[38:41]
	v_mfma_f32_16x16x32_bf16 v[30:33], v[158:161], v[198:201], v[30:33]
	v_mfma_f32_16x16x32_bf16 v[22:25], v[150:153], v[206:209], v[22:25]
	v_mfma_f32_16x16x32_bf16 v[14:17], v[158:161], v[206:209], v[14:17]
	s_setprio 0
	s_setprio 1
	v_mfma_f32_16x16x32_bf16 v[50:53], v[162:165], v[178:181], v[50:53]
	v_mfma_f32_16x16x32_bf16 v[42:45], v[170:173], v[178:181], v[42:45]
	v_mfma_f32_16x16x32_bf16 v[34:37], v[162:165], v[186:189], v[34:37]
	v_mfma_f32_16x16x32_bf16 v[26:29], v[170:173], v[186:189], v[26:29]
	v_mfma_f32_16x16x32_bf16 v[18:21], v[162:165], v[194:197], v[18:21]
	v_mfma_f32_16x16x32_bf16 v[10:13], v[170:173], v[194:197], v[10:13]
	v_mfma_f32_16x16x32_bf16 v[6:9], v[162:165], v[202:205], v[6:9]
	v_mfma_f32_16x16x32_bf16 v[2:5], v[170:173], v[202:205], v[2:5]
	v_mfma_f32_16x16x32_bf16 v[50:53], v[166:169], v[182:185], v[50:53]
	v_mfma_f32_16x16x32_bf16 v[42:45], v[174:177], v[182:185], v[42:45]
	v_mfma_f32_16x16x32_bf16 v[34:37], v[166:169], v[190:193], v[34:37]
	v_mfma_f32_16x16x32_bf16 v[26:29], v[174:177], v[190:193], v[26:29]
	v_mfma_f32_16x16x32_bf16 v[18:21], v[166:169], v[198:201], v[18:21]
	v_mfma_f32_16x16x32_bf16 v[10:13], v[174:177], v[198:201], v[10:13]
	v_mfma_f32_16x16x32_bf16 v[6:9], v[166:169], v[206:209], v[6:9]
	v_mfma_f32_16x16x32_bf16 v[2:5], v[174:177], v[206:209], v[2:5]
	s_setprio 0
	s_barrier
	s_add_i32 s61, 0, 0x18000
	s_add_i32 s64, 0, 0x1c000
	v_add_u32_e32 v158, s61, v143
	v_add_u32_e32 v174, s64, v143
	ds_read_b128 v[146:149], v158
	ds_read_b128 v[150:153], v158 offset:1024
	ds_read_b128 v[154:157], v158 offset:2048
	ds_read_b128 v[158:161], v158 offset:3072
	ds_read_b128 v[162:165], v174
	ds_read_b128 v[166:169], v174 offset:1024
	ds_read_b128 v[170:173], v174 offset:2048
	ds_read_b128 v[174:177], v174 offset:3072
	s_add_u32 s62, s72, 0x40000
	s_addc_u32 s63, s73, 0
	s_mov_b32 m0, s29
	v_lshl_add_u64 v[216:217], s[62:63], 0, v[130:131]
	ds_read_b128 v[178:181], v145 offset:32768
	ds_read_b128 v[182:185], v145 offset:33792
	ds_read_b128 v[186:189], v145 offset:34816
	ds_read_b128 v[190:193], v145 offset:35840
	ds_read_b128 v[194:197], v145 offset:36864
	ds_read_b128 v[198:201], v145 offset:37888
	ds_read_b128 v[202:205], v145 offset:38912
	ds_read_b128 v[206:209], v145 offset:39936
	global_load_lds_dwordx4 v[216:217], off
	v_lshl_add_u64 v[216:217], s[62:63], 0, v[132:133]
	s_mov_b32 m0, s34
	s_nop 0
	global_load_lds_dwordx4 v[216:217], off
	s_waitcnt vmcnt(8)
	s_waitcnt lgkmcnt(0)
	s_barrier
	s_setprio 1
	s_waitcnt lgkmcnt(0)
	v_mfma_f32_16x16x32_bf16 v[126:129], v[146:149], v[178:181], v[126:129]
	v_mfma_f32_16x16x32_bf16 v[122:125], v[154:157], v[178:181], v[122:125]
	v_mfma_f32_16x16x32_bf16 v[118:121], v[146:149], v[186:189], v[118:121]
	v_mfma_f32_16x16x32_bf16 v[110:113], v[154:157], v[186:189], v[110:113]
	v_mfma_f32_16x16x32_bf16 v[102:105], v[146:149], v[194:197], v[102:105]
	v_mfma_f32_16x16x32_bf16 v[94:97], v[154:157], v[194:197], v[94:97]
	v_mfma_f32_16x16x32_bf16 v[86:89], v[146:149], v[202:205], v[86:89]
	v_mfma_f32_16x16x32_bf16 v[78:81], v[154:157], v[202:205], v[78:81]
	v_mfma_f32_16x16x32_bf16 v[126:129], v[150:153], v[182:185], v[126:129]
	v_mfma_f32_16x16x32_bf16 v[122:125], v[158:161], v[182:185], v[122:125]
	v_mfma_f32_16x16x32_bf16 v[118:121], v[150:153], v[190:193], v[118:121]
	v_mfma_f32_16x16x32_bf16 v[110:113], v[158:161], v[190:193], v[110:113]
	v_mfma_f32_16x16x32_bf16 v[102:105], v[150:153], v[198:201], v[102:105]
	v_mfma_f32_16x16x32_bf16 v[94:97], v[158:161], v[198:201], v[94:97]
	v_mfma_f32_16x16x32_bf16 v[86:89], v[150:153], v[206:209], v[86:89]
	v_mfma_f32_16x16x32_bf16 v[78:81], v[158:161], v[206:209], v[78:81]
	s_setprio 0
	s_setprio 1
	v_mfma_f32_16x16x32_bf16 v[114:117], v[162:165], v[178:181], v[114:117]
	v_mfma_f32_16x16x32_bf16 v[106:109], v[170:173], v[178:181], v[106:109]
	v_mfma_f32_16x16x32_bf16 v[98:101], v[162:165], v[186:189], v[98:101]
	v_mfma_f32_16x16x32_bf16 v[90:93], v[170:173], v[186:189], v[90:93]
	v_mfma_f32_16x16x32_bf16 v[82:85], v[162:165], v[194:197], v[82:85]
	v_mfma_f32_16x16x32_bf16 v[74:77], v[170:173], v[194:197], v[74:77]
	v_mfma_f32_16x16x32_bf16 v[70:73], v[162:165], v[202:205], v[70:73]
	v_mfma_f32_16x16x32_bf16 v[66:69], v[170:173], v[202:205], v[66:69]
	v_mfma_f32_16x16x32_bf16 v[114:117], v[166:169], v[182:185], v[114:117]
	v_mfma_f32_16x16x32_bf16 v[106:109], v[174:177], v[182:185], v[106:109]
	v_mfma_f32_16x16x32_bf16 v[98:101], v[166:169], v[190:193], v[98:101]
	v_mfma_f32_16x16x32_bf16 v[90:93], v[174:177], v[190:193], v[90:93]
	v_mfma_f32_16x16x32_bf16 v[82:85], v[166:169], v[198:201], v[82:85]
	v_mfma_f32_16x16x32_bf16 v[74:77], v[174:177], v[198:201], v[74:77]
	v_mfma_f32_16x16x32_bf16 v[70:73], v[166:169], v[206:209], v[70:73]
	v_mfma_f32_16x16x32_bf16 v[66:69], v[174:177], v[206:209], v[66:69]
	s_setprio 0
	s_barrier
; #define PG8_STAGE(bufoff, gbase, voff) do { _Pragma("unroll") for (int _i = 0; _i < 2; ++_i) \
;         __builtin_amdgcn_global_load_lds((const unsigned*)((const char*)(gbase) + (voff)[_i]), (PG8_LAS unsigned*)(lds + (bufoff) + ldsw + _i * 8192), 16, 0, 0); } while (0)
; #define PG8_LDA(dst, b, h) do { _Pragma("unroll") for (int m = 0; m < 4; ++m) _Pragma("unroll") for (int k = 0; k < 2; ++k) dst[m][k] = *(const PG8_LAS bf16x8*)(lds + PG8_SA(b, h) + aoff + m * 2048 + k * 1024); } while (0)
; #define PG8_MMA(ai, bj, At, Bt) do { __builtin_amdgcn_s_setprio(1); _Pragma("unroll") for (int m = 0; m < 4; ++m) _Pragma("unroll") for (int n = 0; n < 2; ++n) _Pragma("unroll") for (int k = 0; k < 2; ++k) \
;         acc[ai][bj][m][n] = __builtin_amdgcn_mfma_f32_16x16x32_bf16(Bt[n][k], At[m][k], acc[ai][bj][m][n], 0, 0, 0); __builtin_amdgcn_s_setprio(0); } while (0)
; #define PG8_WAIT_V(n) asm volatile("s_waitcnt vmcnt(" #n ")" ::: "memory")
; #define PG8_WAIT_L(n) asm volatile("s_waitcnt lgkmcnt(" #n ")" ::: "memory")
; #define PG8_BAR __builtin_amdgcn_s_barrier()
; #define PG8_SCHED __builtin_amdgcn_sched_barrier(0)
; template <class Epi, class Sched, bool ALIGN_EPI = false, bool SP2 = false>
; __device__ __forceinline__ void gemm_phase(PG8_LAS unsigned char* lds, const Gemm g, const Sched& S, const Epi& E, const int tid_in) {
;     ...
;             PG8_LDA(At, 1, 1); PG8_STAGE(PG8_SB(1, 0), b3, voffB); PG8_STAGE(PG8_SB(1, 1), b3 + hstep, voffB); PG8_STAGE(PG8_SA(1, 0), a3, voffA);
;             PG8_WAIT_V(8); PG8_WAIT_L(0); PG8_BAR; PG8_MMA(1, 0, At, B0); PG8_MMA(1, 1, At, B1); PG8_BAR; PG8_SCHED;
	s_add_i32 s61, s61, s26
	v_lshl_add_u64 v[140:141], v[140:141], 0, s[44:45]
	s_mov_b32 m0, s61
	ds_read_b128 v[178:181], v145 offset:49152
	ds_read_b128 v[182:185], v145 offset:50176
	ds_read_b128 v[186:189], v145 offset:51200
	ds_read_b128 v[190:193], v145 offset:52224
	ds_read_b128 v[194:197], v145 offset:53248
	ds_read_b128 v[198:201], v145 offset:54272
	ds_read_b128 v[202:205], v145 offset:55296
	ds_read_b128 v[206:209], v145 offset:56320
	global_load_lds_dwordx4 v[140:141], off
	s_add_i32 m0, s61, 0x2000
	s_add_u32 s62, s70, 0x40080
	v_lshl_add_u64 v[140:141], v[210:211], 0, s[44:45]
	s_addc_u32 s63, s71, 0
	s_add_i32 s61, s64, s26
	global_load_lds_dwordx4 v[140:141], off
	v_lshl_add_u64 v[140:141], s[62:63], 0, v[0:1]
	s_mov_b32 m0, s61
	s_nop 0
	global_load_lds_dwordx4 v[140:141], off
	v_lshl_add_u64 v[140:141], s[62:63], 0, v[134:135]
	s_add_i32 m0, s61, 0x2000
	s_nop 0
	global_load_lds_dwordx4 v[140:141], off
	v_lshl_add_u64 v[140:141], v[212:213], 0, s[44:45]
	s_mov_b32 m0, s35
	s_nop 0
	global_load_lds_dwordx4 v[140:141], off
	v_lshl_add_u64 v[140:141], v[214:215], 0, s[44:45]
	s_mov_b32 m0, s36
	s_nop 0
	global_load_lds_dwordx4 v[140:141], off
	s_waitcnt vmcnt(8)
	s_waitcnt lgkmcnt(0)
	s_barrier
	s_setprio 1
	s_waitcnt lgkmcnt(0)
	v_mfma_f32_16x16x32_bf16 v[62:65], v[146:149], v[178:181], v[62:65]
	v_mfma_f32_16x16x32_bf16 v[58:61], v[154:157], v[178:181], v[58:61]
	v_mfma_f32_16x16x32_bf16 v[54:57], v[146:149], v[186:189], v[54:57]
	v_mfma_f32_16x16x32_bf16 v[46:49], v[154:157], v[186:189], v[46:49]
	v_mfma_f32_16x16x32_bf16 v[38:41], v[146:149], v[194:197], v[38:41]
	v_mfma_f32_16x16x32_bf16 v[30:33], v[154:157], v[194:197], v[30:33]
	v_mfma_f32_16x16x32_bf16 v[22:25], v[146:149], v[202:205], v[22:25]
	v_mfma_f32_16x16x32_bf16 v[14:17], v[154:157], v[202:205], v[14:17]
	v_mfma_f32_16x16x32_bf16 v[62:65], v[150:153], v[182:185], v[62:65]
	v_mfma_f32_16x16x32_bf16 v[58:61], v[158:161], v[182:185], v[58:61]
	v_mfma_f32_16x16x32_bf16 v[54:57], v[150:153], v[190:193], v[54:57]
	v_mfma_f32_16x16x32_bf16 v[46:49], v[158:161], v[190:193], v[46:49]
	v_mfma_f32_16x16x32_bf16 v[38:41], v[150:153], v[198:201], v[38:41]
	v_mfma_f32_16x16x32_bf16 v[30:33], v[158:161], v[198:201], v[30:33]
	v_mfma_f32_16x16x32_bf16 v[22:25], v[150:153], v[206:209], v[22:25]
	v_mfma_f32_16x16x32_bf16 v[14:17], v[158:161], v[206:209], v[14:17]
	s_setprio 0
	s_setprio 1
	v_mfma_f32_16x16x32_bf16 v[50:53], v[162:165], v[178:181], v[50:53]
	v_mfma_f32_16x16x32_bf16 v[42:45], v[170:173], v[178:181], v[42:45]
	v_mfma_f32_16x16x32_bf16 v[34:37], v[162:165], v[186:189], v[34:37]
	v_mfma_f32_16x16x32_bf16 v[26:29], v[170:173], v[186:189], v[26:29]
	v_mfma_f32_16x16x32_bf16 v[18:21], v[162:165], v[194:197], v[18:21]
	v_mfma_f32_16x16x32_bf16 v[10:13], v[170:173], v[194:197], v[10:13]
	v_mfma_f32_16x16x32_bf16 v[6:9], v[162:165], v[202:205], v[6:9]
	v_mfma_f32_16x16x32_bf16 v[2:5], v[170:173], v[202:205], v[2:5]
	v_mfma_f32_16x16x32_bf16 v[50:53], v[166:169], v[182:185], v[50:53]
	v_mfma_f32_16x16x32_bf16 v[42:45], v[174:177], v[182:185], v[42:45]
	v_mfma_f32_16x16x32_bf16 v[34:37], v[166:169], v[190:193], v[34:37]
	v_mfma_f32_16x16x32_bf16 v[26:29], v[174:177], v[190:193], v[26:29]
	v_mfma_f32_16x16x32_bf16 v[18:21], v[166:169], v[198:201], v[18:21]
	v_mfma_f32_16x16x32_bf16 v[10:13], v[174:177], v[198:201], v[10:13]
	v_mfma_f32_16x16x32_bf16 v[6:9], v[166:169], v[206:209], v[6:9]
	v_mfma_f32_16x16x32_bf16 v[2:5], v[174:177], v[206:209], v[2:5]
	s_setprio 0
	s_barrier
	s_add_i32 s60, s60, 2
	s_add_u32 s68, s68, 0x100
	s_addc_u32 s69, s69, 0
	s_add_u32 s58, s58, 0x100
	s_addc_u32 s59, s59, 0
	s_cmp_gt_u32 s60, 13
	s_cbranch_scc0 .LBB0_485
	s_and_b64 vcc, exec, s[10:11]
	s_cbranch_vccz .LBB0_488
	s_barrier

; #define PG8_STAGE(bufoff, gbase, voff) do { _Pragma("unroll") for (int _i = 0; _i < 2; ++_i) \
;         __builtin_amdgcn_global_load_lds((const unsigned*)((const char*)(gbase) + (voff)[_i]), (PG8_LAS unsigned*)(lds + (bufoff) + ldsw + _i * 8192), 16, 0, 0); } while (0)
; #define PG8_LDA(dst, b, h) do { _Pragma("unroll") for (int m = 0; m < 4; ++m) _Pragma("unroll") for (int k = 0; k < 2; ++k) dst[m][k] = *(const PG8_LAS bf16x8*)(lds + PG8_SA(b, h) + aoff + m * 2048 + k * 1024); } while (0)
; #define PG8_LDB(dst, b, h) do { _Pragma("unroll") for (int n = 0; n < 2; ++n) _Pragma("unroll") for (int k = 0; k < 2; ++k) dst[n][k] = *(const PG8_LAS bf16x8*)(lds + PG8_SB(b, h) + boff + n * 2048 + k * 1024); } while (0)
; #define PG8_MMA(ai, bj, At, Bt) do { __builtin_amdgcn_s_setprio(1); _Pragma("unroll") for (int m = 0; m < 4; ++m) _Pragma("unroll") for (int n = 0; n < 2; ++n) _Pragma("unroll") for (int k = 0; k < 2; ++k) \
;         acc[ai][bj][m][n] = __builtin_amdgcn_mfma_f32_16x16x32_bf16(Bt[n][k], At[m][k], acc[ai][bj][m][n], 0, 0, 0); __builtin_amdgcn_s_setprio(0); } while (0)
; #define PG8_BAR __builtin_amdgcn_s_barrier()
; template <class Epi, class Sched, bool ALIGN_EPI = false, bool SP2 = false>
; __device__ __forceinline__ void gemm_phase(PG8_LAS unsigned char* lds, const Gemm g, const Sched& S, const Epi& E, const int tid_in) {
;     ...
;             PG8_LDB(B0, 0, 0); PG8_LDB(B1, 0, 1); PG8_SCHED; PG8_LDA(At, 0, 0); PG8_STAGE(PG8_SA(1, 1), a1 + hstep, voffA);
;             PG8_WAIT_V(8); PG8_WAIT_L(0); PG8_BAR; PG8_MMA(0, 0, At, B0); PG8_MMA(0, 1, At, B1); PG8_BAR; PG8_SCHED;
;             PG8_LDA(At, 0, 1); PG8_STAGE(PG8_SB(0, 0), b2, voffB); PG8_STAGE(PG8_SB(0, 1), b2 + hstep, voffB); PG8_STAGE(PG8_SA(0, 0), a2, voffA);
;             PG8_WAIT_V(8); PG8_WAIT_L(0); PG8_BAR; PG8_MMA(1, 0, At, B0); PG8_MMA(1, 1, At, B1); PG8_BAR; PG8_SCHED;
;             PG8_LDB(B0, 1, 0); PG8_LDB(B1, 1, 1); PG8_SCHED; PG8_LDA(At, 1, 0); PG8_STAGE(PG8_SA(0, 1), a2 + hstep, voffA);
;             PG8_WAIT_V(8); PG8_WAIT_L(0); PG8_BAR; PG8_MMA(0, 0, At, B0); PG8_MMA(0, 1, At, B1); PG8_BAR; PG8_SCHED;
;             PG8_LDA(At, 1, 1); PG8_STAGE(PG8_SB(1, 0), b3, voffB); PG8_STAGE(PG8_SB(1, 1), b3 + hstep, voffB); PG8_STAGE(PG8_SA(1, 0), a3, voffA);
;             PG8_WAIT_V(8); PG8_WAIT_L(0); PG8_BAR; PG8_MMA(1, 0, At, B0); PG8_MMA(1, 1, At, B1); PG8_BAR; PG8_SCHED;
.LBB0_622:
	s_add_u32 s62, s70, 0xfffc0080
	s_addc_u32 s63, s71, -1
	s_add_i32 s64, 0, 0x10000
	s_cmp_eq_u32 s61, 12
	s_cselect_b32 s75, s7, s63
	s_cselect_b32 s74, s43, s62
	v_add_u32_e32 v143, s64, v145
	s_cselect_b32 s73, s19, s60
	s_cselect_b32 s72, s58, s59
	s_add_i32 s76, 0, 0x14000
	ds_read_b128 v[160:163], v143
	ds_read_b128 v[164:167], v143 offset:1024
	ds_read_b128 v[168:171], v143 offset:2048
	ds_read_b128 v[172:175], v143 offset:3072
	v_add_u32_e32 v143, s76, v145
	ds_read_b128 v[176:179], v143
	ds_read_b128 v[180:183], v143 offset:1024
	ds_read_b128 v[184:187], v143 offset:2048
	ds_read_b128 v[188:191], v143 offset:3072
	v_lshl_add_u64 v[154:155], s[70:71], 0, v[136:137]
	s_add_i32 m0, s27, 0xc000
	ds_read_b128 v[192:195], v149
	ds_read_b128 v[196:199], v149 offset:1024
	ds_read_b128 v[200:203], v149 offset:2048
	ds_read_b128 v[204:207], v149 offset:3072
	ds_read_b128 v[208:211], v149 offset:4096
	ds_read_b128 v[212:215], v149 offset:5120
	ds_read_b128 v[216:219], v149 offset:6144
	ds_read_b128 v[220:223], v149 offset:7168
	global_load_lds_dwordx4 v[154:155], off
	v_lshl_add_u64 v[154:155], s[70:71], 0, v[138:139]
	s_add_i32 m0, s27, 0xe000
	s_nop 0
	global_load_lds_dwordx4 v[154:155], off
	s_waitcnt vmcnt(8)
	s_waitcnt lgkmcnt(0)
	s_barrier
	s_setprio 1
	s_waitcnt lgkmcnt(0)
	v_mfma_f32_16x16x32_bf16 v[126:129], v[160:163], v[192:195], v[126:129]
	v_mfma_f32_16x16x32_bf16 v[118:121], v[168:171], v[192:195], v[118:121]
	v_mfma_f32_16x16x32_bf16 v[110:113], v[160:163], v[200:203], v[110:113]
	v_mfma_f32_16x16x32_bf16 v[102:105], v[168:171], v[200:203], v[102:105]
	v_mfma_f32_16x16x32_bf16 v[94:97], v[160:163], v[208:211], v[94:97]
	v_mfma_f32_16x16x32_bf16 v[86:89], v[168:171], v[208:211], v[86:89]
	v_mfma_f32_16x16x32_bf16 v[78:81], v[160:163], v[216:219], v[78:81]
	v_mfma_f32_16x16x32_bf16 v[70:73], v[168:171], v[216:219], v[70:73]
	v_mfma_f32_16x16x32_bf16 v[126:129], v[164:167], v[196:199], v[126:129]
	v_mfma_f32_16x16x32_bf16 v[118:121], v[172:175], v[196:199], v[118:121]
	v_mfma_f32_16x16x32_bf16 v[110:113], v[164:167], v[204:207], v[110:113]
	v_mfma_f32_16x16x32_bf16 v[102:105], v[172:175], v[204:207], v[102:105]
	v_mfma_f32_16x16x32_bf16 v[94:97], v[164:167], v[212:215], v[94:97]
	v_mfma_f32_16x16x32_bf16 v[86:89], v[172:175], v[212:215], v[86:89]
	v_mfma_f32_16x16x32_bf16 v[78:81], v[164:167], v[220:223], v[78:81]
	v_mfma_f32_16x16x32_bf16 v[70:73], v[172:175], v[220:223], v[70:73]
	s_setprio 0
	s_setprio 1
	v_mfma_f32_16x16x32_bf16 v[122:125], v[176:179], v[192:195], v[122:125]
	v_mfma_f32_16x16x32_bf16 v[114:117], v[184:187], v[192:195], v[114:117]
	v_mfma_f32_16x16x32_bf16 v[106:109], v[176:179], v[200:203], v[106:109]
	v_mfma_f32_16x16x32_bf16 v[98:101], v[184:187], v[200:203], v[98:101]
	v_mfma_f32_16x16x32_bf16 v[90:93], v[176:179], v[208:211], v[90:93]
	v_mfma_f32_16x16x32_bf16 v[82:85], v[184:187], v[208:211], v[82:85]
	v_mfma_f32_16x16x32_bf16 v[74:77], v[176:179], v[216:219], v[74:77]
	v_mfma_f32_16x16x32_bf16 v[66:69], v[184:187], v[216:219], v[66:69]
	v_mfma_f32_16x16x32_bf16 v[122:125], v[180:183], v[196:199], v[122:125]
	v_mfma_f32_16x16x32_bf16 v[114:117], v[188:191], v[196:199], v[114:117]
	v_mfma_f32_16x16x32_bf16 v[106:109], v[180:183], v[204:207], v[106:109]
	v_mfma_f32_16x16x32_bf16 v[98:101], v[188:191], v[204:207], v[98:101]
	v_mfma_f32_16x16x32_bf16 v[90:93], v[180:183], v[212:215], v[90:93]
	v_mfma_f32_16x16x32_bf16 v[82:85], v[188:191], v[212:215], v[82:85]
	v_mfma_f32_16x16x32_bf16 v[74:77], v[180:183], v[220:223], v[74:77]
	v_mfma_f32_16x16x32_bf16 v[66:69], v[188:191], v[220:223], v[66:69]
	s_setprio 0
	s_barrier
	s_add_i32 s62, s64, s21
	v_lshl_add_u64 v[154:155], s[72:73], 0, v[0:1]
	s_mov_b32 m0, s62
	ds_read_b128 v[192:195], v149 offset:16384
	ds_read_b128 v[196:199], v149 offset:17408
	ds_read_b128 v[200:203], v149 offset:18432
	ds_read_b128 v[204:207], v149 offset:19456
	ds_read_b128 v[208:211], v149 offset:20480
	ds_read_b128 v[212:215], v149 offset:21504
	ds_read_b128 v[216:219], v149 offset:22528
	ds_read_b128 v[220:223], v149 offset:23552
	global_load_lds_dwordx4 v[154:155], off
	s_add_i32 m0, s62, 0x2000
	s_add_u32 s62, s72, 0x40000
	v_lshl_add_u64 v[224:225], s[72:73], 0, v[130:131]
	s_addc_u32 s63, s73, 0
	s_add_i32 s64, s76, s21
	global_load_lds_dwordx4 v[224:225], off
	v_lshl_add_u64 v[226:227], s[62:63], 0, v[0:1]
	s_mov_b32 m0, s64
	v_lshl_add_u64 v[228:229], s[74:75], 0, v[132:133]
	global_load_lds_dwordx4 v[226:227], off
	v_lshl_add_u64 v[226:227], s[62:63], 0, v[130:131]
	s_add_i32 m0, s64, 0x2000
	s_nop 0
	global_load_lds_dwordx4 v[226:227], off
	v_lshl_add_u64 v[226:227], s[74:75], 0, v[134:135]
	s_mov_b32 m0, s27
	s_nop 0
	global_load_lds_dwordx4 v[226:227], off
	s_mov_b32 m0, s29
	s_nop 0
	global_load_lds_dwordx4 v[228:229], off
	s_waitcnt vmcnt(8)
	s_waitcnt lgkmcnt(0)
	s_barrier
; #define PG8_STAGE(bufoff, gbase, voff) do { _Pragma("unroll") for (int _i = 0; _i < 2; ++_i) \
;         __builtin_amdgcn_global_load_lds((const unsigned*)((const char*)(gbase) + (voff)[_i]), (PG8_LAS unsigned*)(lds + (bufoff) + ldsw + _i * 8192), 16, 0, 0); } while (0)
; #define PG8_LDA(dst, b, h) do { _Pragma("unroll") for (int m = 0; m < 4; ++m) _Pragma("unroll") for (int k = 0; k < 2; ++k) dst[m][k] = *(const PG8_LAS bf16x8*)(lds + PG8_SA(b, h) + aoff + m * 2048 + k * 1024); } while (0)
; #define PG8_LDB(dst, b, h) do { _Pragma("unroll") for (int n = 0; n < 2; ++n) _Pragma("unroll") for (int k = 0; k < 2; ++k) dst[n][k] = *(const PG8_LAS bf16x8*)(lds + PG8_SB(b, h) + boff + n * 2048 + k * 1024); } while (0)
; #define PG8_MMA(ai, bj, At, Bt) do { __builtin_amdgcn_s_setprio(1); _Pragma("unroll") for (int m = 0; m < 4; ++m) _Pragma("unroll") for (int n = 0; n < 2; ++n) _Pragma("unroll") for (int k = 0; k < 2; ++k) \
;         acc[ai][bj][m][n] = __builtin_amdgcn_mfma_f32_16x16x32_bf16(Bt[n][k], At[m][k], acc[ai][bj][m][n], 0, 0, 0); __builtin_amdgcn_s_setprio(0); } while (0)
; #define PG8_BAR __builtin_amdgcn_s_barrier()
; template <class Epi, class Sched, bool ALIGN_EPI = false, bool SP2 = false>
; __device__ __forceinline__ void gemm_phase(PG8_LAS unsigned char* lds, const Gemm g, const Sched& S, const Epi& E, const int tid_in) {
;     ...
;             PG8_LDB(B0, 0, 0); PG8_LDB(B1, 0, 1); PG8_SCHED; PG8_LDA(At, 0, 0); PG8_STAGE(PG8_SA(1, 1), a1 + hstep, voffA);
;             PG8_WAIT_V(8); PG8_WAIT_L(0); PG8_BAR; PG8_MMA(0, 0, At, B0); PG8_MMA(0, 1, At, B1); PG8_BAR; PG8_SCHED;
;             PG8_LDA(At, 0, 1); PG8_STAGE(PG8_SB(0, 0), b2, voffB); PG8_STAGE(PG8_SB(0, 1), b2 + hstep, voffB); PG8_STAGE(PG8_SA(0, 0), a2, voffA);
;             PG8_WAIT_V(8); PG8_WAIT_L(0); PG8_BAR; PG8_MMA(1, 0, At, B0); PG8_MMA(1, 1, At, B1); PG8_BAR; PG8_SCHED;
;             PG8_LDB(B0, 1, 0); PG8_LDB(B1, 1, 1); PG8_SCHED; PG8_LDA(At, 1, 0); PG8_STAGE(PG8_SA(0, 1), a2 + hstep, voffA);
;             PG8_WAIT_V(8); PG8_WAIT_L(0); PG8_BAR; PG8_MMA(0, 0, At, B0); PG8_MMA(0, 1, At, B1); PG8_BAR; PG8_SCHED;
;             PG8_LDA(At, 1, 1); PG8_STAGE(PG8_SB(1, 0), b3, voffB); PG8_STAGE(PG8_SB(1, 1), b3 + hstep, voffB); PG8_STAGE(PG8_SA(1, 0), a3, voffA);
;             PG8_WAIT_V(8); PG8_WAIT_L(0); PG8_BAR; PG8_MMA(1, 0, At, B0); PG8_MMA(1, 1, At, B1); PG8_BAR; PG8_SCHED;
	s_setprio 1
	s_waitcnt lgkmcnt(0)
	v_mfma_f32_16x16x32_bf16 v[62:65], v[160:163], v[192:195], v[62:65]
	v_mfma_f32_16x16x32_bf16 v[54:57], v[168:171], v[192:195], v[54:57]
	v_mfma_f32_16x16x32_bf16 v[46:49], v[160:163], v[200:203], v[46:49]
	v_mfma_f32_16x16x32_bf16 v[38:41], v[168:171], v[200:203], v[38:41]
	v_mfma_f32_16x16x32_bf16 v[30:33], v[160:163], v[208:211], v[30:33]
	v_mfma_f32_16x16x32_bf16 v[22:25], v[168:171], v[208:211], v[22:25]
	v_mfma_f32_16x16x32_bf16 v[14:17], v[160:163], v[216:219], v[14:17]
	v_mfma_f32_16x16x32_bf16 v[6:9], v[168:171], v[216:219], v[6:9]
	v_mfma_f32_16x16x32_bf16 v[62:65], v[164:167], v[196:199], v[62:65]
	v_mfma_f32_16x16x32_bf16 v[54:57], v[172:175], v[196:199], v[54:57]
	v_mfma_f32_16x16x32_bf16 v[46:49], v[164:167], v[204:207], v[46:49]
	v_mfma_f32_16x16x32_bf16 v[38:41], v[172:175], v[204:207], v[38:41]
	v_mfma_f32_16x16x32_bf16 v[30:33], v[164:167], v[212:215], v[30:33]
	v_mfma_f32_16x16x32_bf16 v[22:25], v[172:175], v[212:215], v[22:25]
	v_mfma_f32_16x16x32_bf16 v[14:17], v[164:167], v[220:223], v[14:17]
	v_mfma_f32_16x16x32_bf16 v[6:9], v[172:175], v[220:223], v[6:9]
	s_setprio 0
	s_setprio 1
	v_mfma_f32_16x16x32_bf16 v[58:61], v[176:179], v[192:195], v[58:61]
	v_mfma_f32_16x16x32_bf16 v[50:53], v[184:187], v[192:195], v[50:53]
	v_mfma_f32_16x16x32_bf16 v[42:45], v[176:179], v[200:203], v[42:45]
	v_mfma_f32_16x16x32_bf16 v[34:37], v[184:187], v[200:203], v[34:37]
	v_mfma_f32_16x16x32_bf16 v[26:29], v[176:179], v[208:211], v[26:29]
	v_mfma_f32_16x16x32_bf16 v[18:21], v[184:187], v[208:211], v[18:21]
	v_mfma_f32_16x16x32_bf16 v[10:13], v[176:179], v[216:219], v[10:13]
	v_mfma_f32_16x16x32_bf16 v[2:5], v[184:187], v[216:219], v[2:5]
	v_mfma_f32_16x16x32_bf16 v[58:61], v[180:183], v[196:199], v[58:61]
	v_mfma_f32_16x16x32_bf16 v[50:53], v[188:191], v[196:199], v[50:53]
	v_mfma_f32_16x16x32_bf16 v[42:45], v[180:183], v[204:207], v[42:45]
	v_mfma_f32_16x16x32_bf16 v[34:37], v[188:191], v[204:207], v[34:37]
	v_mfma_f32_16x16x32_bf16 v[26:29], v[180:183], v[212:215], v[26:29]
	v_mfma_f32_16x16x32_bf16 v[18:21], v[188:191], v[212:215], v[18:21]
	v_mfma_f32_16x16x32_bf16 v[10:13], v[180:183], v[220:223], v[10:13]
	v_mfma_f32_16x16x32_bf16 v[2:5], v[188:191], v[220:223], v[2:5]
	s_setprio 0
	s_barrier
	s_add_i32 s64, 0, 0x18000
	v_add_u32_e32 v143, s64, v145
	s_add_i32 s76, 0, 0x1c000
	ds_read_b128 v[160:163], v143
	ds_read_b128 v[164:167], v143 offset:1024
	ds_read_b128 v[168:171], v143 offset:2048
	ds_read_b128 v[172:175], v143 offset:3072
	v_add_u32_e32 v143, s76, v145
	ds_read_b128 v[176:179], v143
	ds_read_b128 v[180:183], v143 offset:1024
	ds_read_b128 v[184:187], v143 offset:2048
	ds_read_b128 v[188:191], v143 offset:3072
	s_add_u32 s62, s74, 0x40000
	s_addc_u32 s63, s75, 0
	s_mov_b32 m0, s34
	v_lshl_add_u64 v[230:231], s[62:63], 0, v[134:135]
	ds_read_b128 v[192:195], v149 offset:32768
	ds_read_b128 v[196:199], v149 offset:33792
	ds_read_b128 v[200:203], v149 offset:34816
	ds_read_b128 v[204:207], v149 offset:35840
	ds_read_b128 v[208:211], v149 offset:36864
	ds_read_b128 v[212:215], v149 offset:37888
	ds_read_b128 v[216:219], v149 offset:38912
	ds_read_b128 v[220:223], v149 offset:39936
	global_load_lds_dwordx4 v[230:231], off
	v_lshl_add_u64 v[230:231], s[62:63], 0, v[132:133]
	s_mov_b32 m0, s35
	s_nop 0
	global_load_lds_dwordx4 v[230:231], off
	s_waitcnt vmcnt(8)
	s_waitcnt lgkmcnt(0)
	s_barrier
	s_setprio 1
	s_waitcnt lgkmcnt(0)
	v_mfma_f32_16x16x32_bf16 v[126:129], v[160:163], v[192:195], v[126:129]
	v_mfma_f32_16x16x32_bf16 v[118:121], v[168:171], v[192:195], v[118:121]
	v_mfma_f32_16x16x32_bf16 v[110:113], v[160:163], v[200:203], v[110:113]
	v_mfma_f32_16x16x32_bf16 v[102:105], v[168:171], v[200:203], v[102:105]
	v_mfma_f32_16x16x32_bf16 v[94:97], v[160:163], v[208:211], v[94:97]
	v_mfma_f32_16x16x32_bf16 v[86:89], v[168:171], v[208:211], v[86:89]
	v_mfma_f32_16x16x32_bf16 v[78:81], v[160:163], v[216:219], v[78:81]
	v_mfma_f32_16x16x32_bf16 v[70:73], v[168:171], v[216:219], v[70:73]
	v_mfma_f32_16x16x32_bf16 v[126:129], v[164:167], v[196:199], v[126:129]
	v_mfma_f32_16x16x32_bf16 v[118:121], v[172:175], v[196:199], v[118:121]
	v_mfma_f32_16x16x32_bf16 v[110:113], v[164:167], v[204:207], v[110:113]
	v_mfma_f32_16x16x32_bf16 v[102:105], v[172:175], v[204:207], v[102:105]
	v_mfma_f32_16x16x32_bf16 v[94:97], v[164:167], v[212:215], v[94:97]
	v_mfma_f32_16x16x32_bf16 v[86:89], v[172:175], v[212:215], v[86:89]
	v_mfma_f32_16x16x32_bf16 v[78:81], v[164:167], v[220:223], v[78:81]
	v_mfma_f32_16x16x32_bf16 v[70:73], v[172:175], v[220:223], v[70:73]
	s_setprio 0
	s_setprio 1
	v_mfma_f32_16x16x32_bf16 v[122:125], v[176:179], v[192:195], v[122:125]
	v_mfma_f32_16x16x32_bf16 v[114:117], v[184:187], v[192:195], v[114:117]
	v_mfma_f32_16x16x32_bf16 v[106:109], v[176:179], v[200:203], v[106:109]
	v_mfma_f32_16x16x32_bf16 v[98:101], v[184:187], v[200:203], v[98:101]
	v_mfma_f32_16x16x32_bf16 v[90:93], v[176:179], v[208:211], v[90:93]
	v_mfma_f32_16x16x32_bf16 v[82:85], v[184:187], v[208:211], v[82:85]
	v_mfma_f32_16x16x32_bf16 v[74:77], v[176:179], v[216:219], v[74:77]
	v_mfma_f32_16x16x32_bf16 v[66:69], v[184:187], v[216:219], v[66:69]
	v_mfma_f32_16x16x32_bf16 v[122:125], v[180:183], v[196:199], v[122:125]
	v_mfma_f32_16x16x32_bf16 v[114:117], v[188:191], v[196:199], v[114:117]
	v_mfma_f32_16x16x32_bf16 v[106:109], v[180:183], v[204:207], v[106:109]
	v_mfma_f32_16x16x32_bf16 v[98:101], v[188:191], v[204:207], v[98:101]
	v_mfma_f32_16x16x32_bf16 v[90:93], v[180:183], v[212:215], v[90:93]
	v_mfma_f32_16x16x32_bf16 v[82:85], v[188:191], v[212:215], v[82:85]
	v_mfma_f32_16x16x32_bf16 v[74:77], v[180:183], v[220:223], v[74:77]
	v_mfma_f32_16x16x32_bf16 v[66:69], v[188:191], v[220:223], v[66:69]
	s_setprio 0
	s_barrier
; #define PG8_STAGE(bufoff, gbase, voff) do { _Pragma("unroll") for (int _i = 0; _i < 2; ++_i) \
;         __builtin_amdgcn_global_load_lds((const unsigned*)((const char*)(gbase) + (voff)[_i]), (PG8_LAS unsigned*)(lds + (bufoff) + ldsw + _i * 8192), 16, 0, 0); } while (0)
; #define PG8_LDA(dst, b, h) do { _Pragma("unroll") for (int m = 0; m < 4; ++m) _Pragma("unroll") for (int k = 0; k < 2; ++k) dst[m][k] = *(const PG8_LAS bf16x8*)(lds + PG8_SA(b, h) + aoff + m * 2048 + k * 1024); } while (0)
; #define PG8_MMA(ai, bj, At, Bt) do { __builtin_amdgcn_s_setprio(1); _Pragma("unroll") for (int m = 0; m < 4; ++m) _Pragma("unroll") for (int n = 0; n < 2; ++n) _Pragma("unroll") for (int k = 0; k < 2; ++k) \
;         acc[ai][bj][m][n] = __builtin_amdgcn_mfma_f32_16x16x32_bf16(Bt[n][k], At[m][k], acc[ai][bj][m][n], 0, 0, 0); __builtin_amdgcn_s_setprio(0); } while (0)
; #define PG8_WAIT_V(n) asm volatile("s_waitcnt vmcnt(" #n ")" ::: "memory")
; #define PG8_WAIT_L(n) asm volatile("s_waitcnt lgkmcnt(" #n ")" ::: "memory")
; #define PG8_BAR __builtin_amdgcn_s_barrier()
; #define PG8_SCHED __builtin_amdgcn_sched_barrier(0)
; template <class Epi, class Sched, bool ALIGN_EPI = false, bool SP2 = false>
; __device__ __forceinline__ void gemm_phase(PG8_LAS unsigned char* lds, const Gemm g, const Sched& S, const Epi& E, const int tid_in) {
;     ...
;             PG8_LDA(At, 1, 1); PG8_STAGE(PG8_SB(1, 0), b3, voffB); PG8_STAGE(PG8_SB(1, 1), b3 + hstep, voffB); PG8_STAGE(PG8_SA(1, 0), a3, voffA);
;             PG8_WAIT_V(8); PG8_WAIT_L(0); PG8_BAR; PG8_MMA(1, 0, At, B0); PG8_MMA(1, 1, At, B1); PG8_BAR; PG8_SCHED;
	s_add_i32 s62, s64, s21
	v_lshl_add_u64 v[154:155], v[154:155], 0, s[44:45]
	s_mov_b32 m0, s62
	ds_read_b128 v[192:195], v149 offset:49152
	ds_read_b128 v[196:199], v149 offset:50176
	ds_read_b128 v[200:203], v149 offset:51200
	ds_read_b128 v[204:207], v149 offset:52224
	ds_read_b128 v[208:211], v149 offset:53248
	ds_read_b128 v[212:215], v149 offset:54272
	ds_read_b128 v[216:219], v149 offset:55296
	ds_read_b128 v[220:223], v149 offset:56320
	global_load_lds_dwordx4 v[154:155], off
	s_add_i32 m0, s62, 0x2000
	s_add_u32 s62, s72, 0x40080
	v_lshl_add_u64 v[154:155], v[224:225], 0, s[44:45]
	s_addc_u32 s63, s73, 0
	s_add_i32 s64, s76, s21
	global_load_lds_dwordx4 v[154:155], off
	v_lshl_add_u64 v[154:155], s[62:63], 0, v[0:1]
	s_mov_b32 m0, s64
	s_nop 0
	global_load_lds_dwordx4 v[154:155], off
	v_lshl_add_u64 v[154:155], s[62:63], 0, v[130:131]
	s_add_i32 m0, s64, 0x2000
	s_nop 0
	global_load_lds_dwordx4 v[154:155], off
	v_lshl_add_u64 v[154:155], v[226:227], 0, s[44:45]
	s_mov_b32 m0, s36
	s_nop 0
	global_load_lds_dwordx4 v[154:155], off
	v_lshl_add_u64 v[154:155], v[228:229], 0, s[44:45]
	s_mov_b32 m0, s37
	s_nop 0
	global_load_lds_dwordx4 v[154:155], off
	s_waitcnt vmcnt(8)
	s_waitcnt lgkmcnt(0)
	s_barrier
	s_setprio 1
	s_waitcnt lgkmcnt(0)
	v_mfma_f32_16x16x32_bf16 v[62:65], v[160:163], v[192:195], v[62:65]
	v_mfma_f32_16x16x32_bf16 v[54:57], v[168:171], v[192:195], v[54:57]
	v_mfma_f32_16x16x32_bf16 v[46:49], v[160:163], v[200:203], v[46:49]
	v_mfma_f32_16x16x32_bf16 v[38:41], v[168:171], v[200:203], v[38:41]
	v_mfma_f32_16x16x32_bf16 v[30:33], v[160:163], v[208:211], v[30:33]
	v_mfma_f32_16x16x32_bf16 v[22:25], v[168:171], v[208:211], v[22:25]
	v_mfma_f32_16x16x32_bf16 v[14:17], v[160:163], v[216:219], v[14:17]
	v_mfma_f32_16x16x32_bf16 v[6:9], v[168:171], v[216:219], v[6:9]
	v_mfma_f32_16x16x32_bf16 v[62:65], v[164:167], v[196:199], v[62:65]
	v_mfma_f32_16x16x32_bf16 v[54:57], v[172:175], v[196:199], v[54:57]
	v_mfma_f32_16x16x32_bf16 v[46:49], v[164:167], v[204:207], v[46:49]
	v_mfma_f32_16x16x32_bf16 v[38:41], v[172:175], v[204:207], v[38:41]
	v_mfma_f32_16x16x32_bf16 v[30:33], v[164:167], v[212:215], v[30:33]
	v_mfma_f32_16x16x32_bf16 v[22:25], v[172:175], v[212:215], v[22:25]
	v_mfma_f32_16x16x32_bf16 v[14:17], v[164:167], v[220:223], v[14:17]
	v_mfma_f32_16x16x32_bf16 v[6:9], v[172:175], v[220:223], v[6:9]
	s_setprio 0
	s_setprio 1
	v_mfma_f32_16x16x32_bf16 v[58:61], v[176:179], v[192:195], v[58:61]
	v_mfma_f32_16x16x32_bf16 v[50:53], v[184:187], v[192:195], v[50:53]
	v_mfma_f32_16x16x32_bf16 v[42:45], v[176:179], v[200:203], v[42:45]
	v_mfma_f32_16x16x32_bf16 v[34:37], v[184:187], v[200:203], v[34:37]
	v_mfma_f32_16x16x32_bf16 v[26:29], v[176:179], v[208:211], v[26:29]
	v_mfma_f32_16x16x32_bf16 v[18:21], v[184:187], v[208:211], v[18:21]
	v_mfma_f32_16x16x32_bf16 v[10:13], v[176:179], v[216:219], v[10:13]
	v_mfma_f32_16x16x32_bf16 v[2:5], v[184:187], v[216:219], v[2:5]
	v_mfma_f32_16x16x32_bf16 v[58:61], v[180:183], v[196:199], v[58:61]
	v_mfma_f32_16x16x32_bf16 v[50:53], v[188:191], v[196:199], v[50:53]
	v_mfma_f32_16x16x32_bf16 v[42:45], v[180:183], v[204:207], v[42:45]
	v_mfma_f32_16x16x32_bf16 v[34:37], v[188:191], v[204:207], v[34:37]
	v_mfma_f32_16x16x32_bf16 v[26:29], v[180:183], v[212:215], v[26:29]
	v_mfma_f32_16x16x32_bf16 v[18:21], v[188:191], v[212:215], v[18:21]
	v_mfma_f32_16x16x32_bf16 v[10:13], v[180:183], v[220:223], v[10:13]
	v_mfma_f32_16x16x32_bf16 v[2:5], v[188:191], v[220:223], v[2:5]
	s_setprio 0
	s_barrier
	s_add_i32 s61, s61, 2
	s_add_u32 s70, s70, 0x100
	s_addc_u32 s71, s71, 0
	s_add_u32 s59, s59, 0x100
	s_addc_u32 s60, s60, 0
	s_cmp_gt_u32 s61, 13
	s_cbranch_scc0 .LBB0_622
	s_and_b64 vcc, exec, s[16:17]
	s_cbranch_vccz .LBB0_625
	s_barrier

; #define PG8_STAGE(bufoff, gbase, voff) do { _Pragma("unroll") for (int _i = 0; _i < 2; ++_i) \
;         __builtin_amdgcn_global_load_lds((const unsigned*)((const char*)(gbase) + (voff)[_i]), (PG8_LAS unsigned*)(lds + (bufoff) + ldsw + _i * 8192), 16, 0, 0); } while (0)
; #define PG8_LDA(dst, b, h) do { _Pragma("unroll") for (int m = 0; m < 4; ++m) _Pragma("unroll") for (int k = 0; k < 2; ++k) dst[m][k] = *(const PG8_LAS bf16x8*)(lds + PG8_SA(b, h) + aoff + m * 2048 + k * 1024); } while (0)
; #define PG8_LDB(dst, b, h) do { _Pragma("unroll") for (int n = 0; n < 2; ++n) _Pragma("unroll") for (int k = 0; k < 2; ++k) dst[n][k] = *(const PG8_LAS bf16x8*)(lds + PG8_SB(b, h) + boff + n * 2048 + k * 1024); } while (0)
; #define PG8_MMA(ai, bj, At, Bt) do { __builtin_amdgcn_s_setprio(1); _Pragma("unroll") for (int m = 0; m < 4; ++m) _Pragma("unroll") for (int n = 0; n < 2; ++n) _Pragma("unroll") for (int k = 0; k < 2; ++k) \
;         acc[ai][bj][m][n] = __builtin_amdgcn_mfma_f32_16x16x32_bf16(Bt[n][k], At[m][k], acc[ai][bj][m][n], 0, 0, 0); __builtin_amdgcn_s_setprio(0); } while (0)
; #define PG8_BAR __builtin_amdgcn_s_barrier()
; template <class Epi, class Sched, bool ALIGN_EPI = false, bool SP2 = false>
; __device__ __forceinline__ void gemm_phase(PG8_LAS unsigned char* lds, const Gemm g, const Sched& S, const Epi& E, const int tid_in) {
;     ...
;             PG8_LDB(B0, 0, 0); PG8_LDB(B1, 0, 1); PG8_SCHED; PG8_LDA(At, 0, 0); PG8_STAGE(PG8_SA(1, 1), a1 + hstep, voffA);
;             PG8_WAIT_V(8); PG8_WAIT_L(0); PG8_BAR; PG8_MMA(0, 0, At, B0); PG8_MMA(0, 1, At, B1); PG8_BAR; PG8_SCHED;
;             PG8_LDA(At, 0, 1); PG8_STAGE(PG8_SB(0, 0), b2, voffB); PG8_STAGE(PG8_SB(0, 1), b2 + hstep, voffB); PG8_STAGE(PG8_SA(0, 0), a2, voffA);
;             PG8_WAIT_V(8); PG8_WAIT_L(0); PG8_BAR; PG8_MMA(1, 0, At, B0); PG8_MMA(1, 1, At, B1); PG8_BAR; PG8_SCHED;
;             PG8_LDB(B0, 1, 0); PG8_LDB(B1, 1, 1); PG8_SCHED; PG8_LDA(At, 1, 0); PG8_STAGE(PG8_SA(0, 1), a2 + hstep, voffA);
;             PG8_WAIT_V(8); PG8_WAIT_L(0); PG8_BAR; PG8_MMA(0, 0, At, B0); PG8_MMA(0, 1, At, B1); PG8_BAR; PG8_SCHED;
;             PG8_LDA(At, 1, 1); PG8_STAGE(PG8_SB(1, 0), b3, voffB); PG8_STAGE(PG8_SB(1, 1), b3 + hstep, voffB); PG8_STAGE(PG8_SA(1, 0), a3, voffA);
;             PG8_WAIT_V(8); PG8_WAIT_L(0); PG8_BAR; PG8_MMA(1, 0, At, B0); PG8_MMA(1, 1, At, B1); PG8_BAR; PG8_SCHED;
.LBB0_703:
	s_add_u32 s20, s18, 0x100
	s_addc_u32 s21, s19, 0
	s_add_i32 s70, 0, 0x10000
	s_cmp_eq_u32 s64, 40
	s_cselect_b32 s69, s5, s21
	s_cselect_b32 s68, s4, s20
	v_add_u32_e32 v140, s70, v143
	s_cselect_b32 s23, s17, s63
	s_cselect_b32 s22, s16, s62
	s_add_i32 s71, 0, 0x14000
	ds_read_b128 v[146:149], v140
	ds_read_b128 v[150:153], v140 offset:1024
	ds_read_b128 v[154:157], v140 offset:2048
	ds_read_b128 v[158:161], v140 offset:3072
	v_add_u32_e32 v140, s71, v143
	ds_read_b128 v[162:165], v140
	ds_read_b128 v[166:169], v140 offset:1024
	ds_read_b128 v[170:173], v140 offset:2048
	ds_read_b128 v[174:177], v140 offset:3072
	v_lshl_add_u64 v[140:141], s[18:19], 0, v[136:137]
	s_add_i32 m0, s34, 0xc000
	ds_read_b128 v[178:181], v145
	ds_read_b128 v[182:185], v145 offset:1024
	ds_read_b128 v[186:189], v145 offset:2048
	ds_read_b128 v[190:193], v145 offset:3072
	ds_read_b128 v[194:197], v145 offset:4096
	ds_read_b128 v[198:201], v145 offset:5120
	ds_read_b128 v[202:205], v145 offset:6144
	ds_read_b128 v[206:209], v145 offset:7168
	global_load_lds_dwordx4 v[140:141], off
	v_lshl_add_u64 v[140:141], s[18:19], 0, v[138:139]
	s_add_i32 m0, s34, 0xe000
	s_nop 0
	global_load_lds_dwordx4 v[140:141], off
	s_waitcnt vmcnt(8)
	s_waitcnt lgkmcnt(0)
	s_barrier
	s_setprio 1
	s_waitcnt lgkmcnt(0)
	v_mfma_f32_16x16x32_bf16 v[126:129], v[146:149], v[178:181], v[126:129]
	v_mfma_f32_16x16x32_bf16 v[122:125], v[154:157], v[178:181], v[122:125]
	v_mfma_f32_16x16x32_bf16 v[118:121], v[146:149], v[186:189], v[118:121]
	v_mfma_f32_16x16x32_bf16 v[110:113], v[154:157], v[186:189], v[110:113]
	v_mfma_f32_16x16x32_bf16 v[102:105], v[146:149], v[194:197], v[102:105]
	v_mfma_f32_16x16x32_bf16 v[94:97], v[154:157], v[194:197], v[94:97]
	v_mfma_f32_16x16x32_bf16 v[86:89], v[146:149], v[202:205], v[86:89]
	v_mfma_f32_16x16x32_bf16 v[78:81], v[154:157], v[202:205], v[78:81]
	v_mfma_f32_16x16x32_bf16 v[126:129], v[150:153], v[182:185], v[126:129]
	v_mfma_f32_16x16x32_bf16 v[122:125], v[158:161], v[182:185], v[122:125]
	v_mfma_f32_16x16x32_bf16 v[118:121], v[150:153], v[190:193], v[118:121]
	v_mfma_f32_16x16x32_bf16 v[110:113], v[158:161], v[190:193], v[110:113]
	v_mfma_f32_16x16x32_bf16 v[102:105], v[150:153], v[198:201], v[102:105]
	v_mfma_f32_16x16x32_bf16 v[94:97], v[158:161], v[198:201], v[94:97]
	v_mfma_f32_16x16x32_bf16 v[86:89], v[150:153], v[206:209], v[86:89]
	v_mfma_f32_16x16x32_bf16 v[78:81], v[158:161], v[206:209], v[78:81]
	s_setprio 0
	s_setprio 1
	v_mfma_f32_16x16x32_bf16 v[114:117], v[162:165], v[178:181], v[114:117]
	v_mfma_f32_16x16x32_bf16 v[106:109], v[170:173], v[178:181], v[106:109]
	v_mfma_f32_16x16x32_bf16 v[98:101], v[162:165], v[186:189], v[98:101]
	v_mfma_f32_16x16x32_bf16 v[90:93], v[170:173], v[186:189], v[90:93]
	v_mfma_f32_16x16x32_bf16 v[82:85], v[162:165], v[194:197], v[82:85]
	v_mfma_f32_16x16x32_bf16 v[74:77], v[170:173], v[194:197], v[74:77]
	v_mfma_f32_16x16x32_bf16 v[70:73], v[162:165], v[202:205], v[70:73]
	v_mfma_f32_16x16x32_bf16 v[66:69], v[170:173], v[202:205], v[66:69]
	v_mfma_f32_16x16x32_bf16 v[114:117], v[166:169], v[182:185], v[114:117]
	v_mfma_f32_16x16x32_bf16 v[106:109], v[174:177], v[182:185], v[106:109]
	v_mfma_f32_16x16x32_bf16 v[98:101], v[166:169], v[190:193], v[98:101]
	v_mfma_f32_16x16x32_bf16 v[90:93], v[174:177], v[190:193], v[90:93]
	v_mfma_f32_16x16x32_bf16 v[82:85], v[166:169], v[198:201], v[82:85]
	v_mfma_f32_16x16x32_bf16 v[74:77], v[174:177], v[198:201], v[74:77]
	v_mfma_f32_16x16x32_bf16 v[70:73], v[166:169], v[206:209], v[70:73]
	v_mfma_f32_16x16x32_bf16 v[66:69], v[174:177], v[206:209], v[66:69]
	s_setprio 0
	s_barrier
	s_add_i32 s18, s70, s29
	v_lshl_add_u64 v[140:141], s[22:23], 0, v[0:1]
	s_mov_b32 m0, s18
	ds_read_b128 v[178:181], v145 offset:16384
	ds_read_b128 v[182:185], v145 offset:17408
	ds_read_b128 v[186:189], v145 offset:18432
	ds_read_b128 v[190:193], v145 offset:19456
	ds_read_b128 v[194:197], v145 offset:20480
	ds_read_b128 v[198:201], v145 offset:21504
	ds_read_b128 v[202:205], v145 offset:22528
	ds_read_b128 v[206:209], v145 offset:23552
	global_load_lds_dwordx4 v[140:141], off
	s_add_i32 m0, s18, 0x2000
	s_add_u32 s18, s22, 0xb0000
	v_lshl_add_u64 v[210:211], s[22:23], 0, v[134:135]
	s_addc_u32 s19, s23, 0
	s_add_i32 s70, s71, s29
	global_load_lds_dwordx4 v[210:211], off
	v_lshl_add_u64 v[212:213], s[18:19], 0, v[0:1]
	s_mov_b32 m0, s70
	v_lshl_add_u64 v[214:215], s[68:69], 0, v[132:133]
	global_load_lds_dwordx4 v[212:213], off
	v_lshl_add_u64 v[212:213], s[18:19], 0, v[134:135]
	s_add_i32 m0, s70, 0x2000
	s_nop 0
	global_load_lds_dwordx4 v[212:213], off
	v_lshl_add_u64 v[212:213], s[68:69], 0, v[130:131]
	s_mov_b32 m0, s34
	s_nop 0
	global_load_lds_dwordx4 v[212:213], off
	s_mov_b32 m0, s35
	s_nop 0
	global_load_lds_dwordx4 v[214:215], off
	s_waitcnt vmcnt(8)
	s_waitcnt lgkmcnt(0)
	s_barrier
; #define PG8_STAGE(bufoff, gbase, voff) do { _Pragma("unroll") for (int _i = 0; _i < 2; ++_i) \
;         __builtin_amdgcn_global_load_lds((const unsigned*)((const char*)(gbase) + (voff)[_i]), (PG8_LAS unsigned*)(lds + (bufoff) + ldsw + _i * 8192), 16, 0, 0); } while (0)
; #define PG8_LDA(dst, b, h) do { _Pragma("unroll") for (int m = 0; m < 4; ++m) _Pragma("unroll") for (int k = 0; k < 2; ++k) dst[m][k] = *(const PG8_LAS bf16x8*)(lds + PG8_SA(b, h) + aoff + m * 2048 + k * 1024); } while (0)
; #define PG8_LDB(dst, b, h) do { _Pragma("unroll") for (int n = 0; n < 2; ++n) _Pragma("unroll") for (int k = 0; k < 2; ++k) dst[n][k] = *(const PG8_LAS bf16x8*)(lds + PG8_SB(b, h) + boff + n * 2048 + k * 1024); } while (0)
; #define PG8_MMA(ai, bj, At, Bt) do { __builtin_amdgcn_s_setprio(1); _Pragma("unroll") for (int m = 0; m < 4; ++m) _Pragma("unroll") for (int n = 0; n < 2; ++n) _Pragma("unroll") for (int k = 0; k < 2; ++k) \
;         acc[ai][bj][m][n] = __builtin_amdgcn_mfma_f32_16x16x32_bf16(Bt[n][k], At[m][k], acc[ai][bj][m][n], 0, 0, 0); __builtin_amdgcn_s_setprio(0); } while (0)
; #define PG8_BAR __builtin_amdgcn_s_barrier()
; template <class Epi, class Sched, bool ALIGN_EPI = false, bool SP2 = false>
; __device__ __forceinline__ void gemm_phase(PG8_LAS unsigned char* lds, const Gemm g, const Sched& S, const Epi& E, const int tid_in) {
;     ...
;             PG8_LDB(B0, 0, 0); PG8_LDB(B1, 0, 1); PG8_SCHED; PG8_LDA(At, 0, 0); PG8_STAGE(PG8_SA(1, 1), a1 + hstep, voffA);
;             PG8_WAIT_V(8); PG8_WAIT_L(0); PG8_BAR; PG8_MMA(0, 0, At, B0); PG8_MMA(0, 1, At, B1); PG8_BAR; PG8_SCHED;
;             PG8_LDA(At, 0, 1); PG8_STAGE(PG8_SB(0, 0), b2, voffB); PG8_STAGE(PG8_SB(0, 1), b2 + hstep, voffB); PG8_STAGE(PG8_SA(0, 0), a2, voffA);
;             PG8_WAIT_V(8); PG8_WAIT_L(0); PG8_BAR; PG8_MMA(1, 0, At, B0); PG8_MMA(1, 1, At, B1); PG8_BAR; PG8_SCHED;
;             PG8_LDB(B0, 1, 0); PG8_LDB(B1, 1, 1); PG8_SCHED; PG8_LDA(At, 1, 0); PG8_STAGE(PG8_SA(0, 1), a2 + hstep, voffA);
;             PG8_WAIT_V(8); PG8_WAIT_L(0); PG8_BAR; PG8_MMA(0, 0, At, B0); PG8_MMA(0, 1, At, B1); PG8_BAR; PG8_SCHED;
;             PG8_LDA(At, 1, 1); PG8_STAGE(PG8_SB(1, 0), b3, voffB); PG8_STAGE(PG8_SB(1, 1), b3 + hstep, voffB); PG8_STAGE(PG8_SA(1, 0), a3, voffA);
;             PG8_WAIT_V(8); PG8_WAIT_L(0); PG8_BAR; PG8_MMA(1, 0, At, B0); PG8_MMA(1, 1, At, B1); PG8_BAR; PG8_SCHED;
	s_setprio 1
	s_waitcnt lgkmcnt(0)
	v_mfma_f32_16x16x32_bf16 v[62:65], v[146:149], v[178:181], v[62:65]
	v_mfma_f32_16x16x32_bf16 v[58:61], v[154:157], v[178:181], v[58:61]
	v_mfma_f32_16x16x32_bf16 v[54:57], v[146:149], v[186:189], v[54:57]
	v_mfma_f32_16x16x32_bf16 v[46:49], v[154:157], v[186:189], v[46:49]
	v_mfma_f32_16x16x32_bf16 v[38:41], v[146:149], v[194:197], v[38:41]
	v_mfma_f32_16x16x32_bf16 v[30:33], v[154:157], v[194:197], v[30:33]
	v_mfma_f32_16x16x32_bf16 v[22:25], v[146:149], v[202:205], v[22:25]
	v_mfma_f32_16x16x32_bf16 v[14:17], v[154:157], v[202:205], v[14:17]
	v_mfma_f32_16x16x32_bf16 v[62:65], v[150:153], v[182:185], v[62:65]
	v_mfma_f32_16x16x32_bf16 v[58:61], v[158:161], v[182:185], v[58:61]
	v_mfma_f32_16x16x32_bf16 v[54:57], v[150:153], v[190:193], v[54:57]
	v_mfma_f32_16x16x32_bf16 v[46:49], v[158:161], v[190:193], v[46:49]
	v_mfma_f32_16x16x32_bf16 v[38:41], v[150:153], v[198:201], v[38:41]
	v_mfma_f32_16x16x32_bf16 v[30:33], v[158:161], v[198:201], v[30:33]
	v_mfma_f32_16x16x32_bf16 v[22:25], v[150:153], v[206:209], v[22:25]
	v_mfma_f32_16x16x32_bf16 v[14:17], v[158:161], v[206:209], v[14:17]
	s_setprio 0
	s_setprio 1
	v_mfma_f32_16x16x32_bf16 v[50:53], v[162:165], v[178:181], v[50:53]
	v_mfma_f32_16x16x32_bf16 v[42:45], v[170:173], v[178:181], v[42:45]
	v_mfma_f32_16x16x32_bf16 v[34:37], v[162:165], v[186:189], v[34:37]
	v_mfma_f32_16x16x32_bf16 v[26:29], v[170:173], v[186:189], v[26:29]
	v_mfma_f32_16x16x32_bf16 v[18:21], v[162:165], v[194:197], v[18:21]
	v_mfma_f32_16x16x32_bf16 v[10:13], v[170:173], v[194:197], v[10:13]
	v_mfma_f32_16x16x32_bf16 v[6:9], v[162:165], v[202:205], v[6:9]
	v_mfma_f32_16x16x32_bf16 v[2:5], v[170:173], v[202:205], v[2:5]
	v_mfma_f32_16x16x32_bf16 v[50:53], v[166:169], v[182:185], v[50:53]
	v_mfma_f32_16x16x32_bf16 v[42:45], v[174:177], v[182:185], v[42:45]
	v_mfma_f32_16x16x32_bf16 v[34:37], v[166:169], v[190:193], v[34:37]
	v_mfma_f32_16x16x32_bf16 v[26:29], v[174:177], v[190:193], v[26:29]
	v_mfma_f32_16x16x32_bf16 v[18:21], v[166:169], v[198:201], v[18:21]
	v_mfma_f32_16x16x32_bf16 v[10:13], v[174:177], v[198:201], v[10:13]
	v_mfma_f32_16x16x32_bf16 v[6:9], v[166:169], v[206:209], v[6:9]
	v_mfma_f32_16x16x32_bf16 v[2:5], v[174:177], v[206:209], v[2:5]
	s_setprio 0
	s_barrier
	s_add_i32 s70, 0, 0x18000
	s_add_i32 s71, 0, 0x1c000
	v_add_u32_e32 v158, s70, v143
	v_add_u32_e32 v174, s71, v143
	ds_read_b128 v[146:149], v158
	ds_read_b128 v[150:153], v158 offset:1024
	ds_read_b128 v[154:157], v158 offset:2048
	ds_read_b128 v[158:161], v158 offset:3072
	ds_read_b128 v[162:165], v174
	ds_read_b128 v[166:169], v174 offset:1024
	ds_read_b128 v[170:173], v174 offset:2048
	ds_read_b128 v[174:177], v174 offset:3072
	s_add_u32 s18, s68, 0xb0000
	s_addc_u32 s19, s69, 0
	s_mov_b32 m0, s36
	v_lshl_add_u64 v[216:217], s[18:19], 0, v[130:131]
	ds_read_b128 v[178:181], v145 offset:32768
	ds_read_b128 v[182:185], v145 offset:33792
	ds_read_b128 v[186:189], v145 offset:34816
	ds_read_b128 v[190:193], v145 offset:35840
	ds_read_b128 v[194:197], v145 offset:36864
	ds_read_b128 v[198:201], v145 offset:37888
	ds_read_b128 v[202:205], v145 offset:38912
	ds_read_b128 v[206:209], v145 offset:39936
	global_load_lds_dwordx4 v[216:217], off
	v_lshl_add_u64 v[216:217], s[18:19], 0, v[132:133]
	s_mov_b32 m0, s37
	s_nop 0
	global_load_lds_dwordx4 v[216:217], off
	s_waitcnt vmcnt(8)
	s_waitcnt lgkmcnt(0)
	s_barrier
	s_setprio 1
	s_waitcnt lgkmcnt(0)
	v_mfma_f32_16x16x32_bf16 v[126:129], v[146:149], v[178:181], v[126:129]
	v_mfma_f32_16x16x32_bf16 v[122:125], v[154:157], v[178:181], v[122:125]
	v_mfma_f32_16x16x32_bf16 v[118:121], v[146:149], v[186:189], v[118:121]
	v_mfma_f32_16x16x32_bf16 v[110:113], v[154:157], v[186:189], v[110:113]
	v_mfma_f32_16x16x32_bf16 v[102:105], v[146:149], v[194:197], v[102:105]
	v_mfma_f32_16x16x32_bf16 v[94:97], v[154:157], v[194:197], v[94:97]
	v_mfma_f32_16x16x32_bf16 v[86:89], v[146:149], v[202:205], v[86:89]
	v_mfma_f32_16x16x32_bf16 v[78:81], v[154:157], v[202:205], v[78:81]
	v_mfma_f32_16x16x32_bf16 v[126:129], v[150:153], v[182:185], v[126:129]
	v_mfma_f32_16x16x32_bf16 v[122:125], v[158:161], v[182:185], v[122:125]
	v_mfma_f32_16x16x32_bf16 v[118:121], v[150:153], v[190:193], v[118:121]
	v_mfma_f32_16x16x32_bf16 v[110:113], v[158:161], v[190:193], v[110:113]
	v_mfma_f32_16x16x32_bf16 v[102:105], v[150:153], v[198:201], v[102:105]
	v_mfma_f32_16x16x32_bf16 v[94:97], v[158:161], v[198:201], v[94:97]
	v_mfma_f32_16x16x32_bf16 v[86:89], v[150:153], v[206:209], v[86:89]
	v_mfma_f32_16x16x32_bf16 v[78:81], v[158:161], v[206:209], v[78:81]
	s_setprio 0
	s_setprio 1
	v_mfma_f32_16x16x32_bf16 v[114:117], v[162:165], v[178:181], v[114:117]
	v_mfma_f32_16x16x32_bf16 v[106:109], v[170:173], v[178:181], v[106:109]
	v_mfma_f32_16x16x32_bf16 v[98:101], v[162:165], v[186:189], v[98:101]
	v_mfma_f32_16x16x32_bf16 v[90:93], v[170:173], v[186:189], v[90:93]
	v_mfma_f32_16x16x32_bf16 v[82:85], v[162:165], v[194:197], v[82:85]
	v_mfma_f32_16x16x32_bf16 v[74:77], v[170:173], v[194:197], v[74:77]
	v_mfma_f32_16x16x32_bf16 v[70:73], v[162:165], v[202:205], v[70:73]
	v_mfma_f32_16x16x32_bf16 v[66:69], v[170:173], v[202:205], v[66:69]
	v_mfma_f32_16x16x32_bf16 v[114:117], v[166:169], v[182:185], v[114:117]
	v_mfma_f32_16x16x32_bf16 v[106:109], v[174:177], v[182:185], v[106:109]
	v_mfma_f32_16x16x32_bf16 v[98:101], v[166:169], v[190:193], v[98:101]
	v_mfma_f32_16x16x32_bf16 v[90:93], v[174:177], v[190:193], v[90:93]
	v_mfma_f32_16x16x32_bf16 v[82:85], v[166:169], v[198:201], v[82:85]
	v_mfma_f32_16x16x32_bf16 v[74:77], v[174:177], v[198:201], v[74:77]
	v_mfma_f32_16x16x32_bf16 v[70:73], v[166:169], v[206:209], v[70:73]
	v_mfma_f32_16x16x32_bf16 v[66:69], v[174:177], v[206:209], v[66:69]
	s_setprio 0
	s_barrier
; #define PG8_STAGE(bufoff, gbase, voff) do { _Pragma("unroll") for (int _i = 0; _i < 2; ++_i) \
;         __builtin_amdgcn_global_load_lds((const unsigned*)((const char*)(gbase) + (voff)[_i]), (PG8_LAS unsigned*)(lds + (bufoff) + ldsw + _i * 8192), 16, 0, 0); } while (0)
; #define PG8_LDA(dst, b, h) do { _Pragma("unroll") for (int m = 0; m < 4; ++m) _Pragma("unroll") for (int k = 0; k < 2; ++k) dst[m][k] = *(const PG8_LAS bf16x8*)(lds + PG8_SA(b, h) + aoff + m * 2048 + k * 1024); } while (0)
; #define PG8_MMA(ai, bj, At, Bt) do { __builtin_amdgcn_s_setprio(1); _Pragma("unroll") for (int m = 0; m < 4; ++m) _Pragma("unroll") for (int n = 0; n < 2; ++n) _Pragma("unroll") for (int k = 0; k < 2; ++k) \
;         acc[ai][bj][m][n] = __builtin_amdgcn_mfma_f32_16x16x32_bf16(Bt[n][k], At[m][k], acc[ai][bj][m][n], 0, 0, 0); __builtin_amdgcn_s_setprio(0); } while (0)
; #define PG8_WAIT_V(n) asm volatile("s_waitcnt vmcnt(" #n ")" ::: "memory")
; #define PG8_WAIT_L(n) asm volatile("s_waitcnt lgkmcnt(" #n ")" ::: "memory")
; #define PG8_BAR __builtin_amdgcn_s_barrier()
; #define PG8_SCHED __builtin_amdgcn_sched_barrier(0)
; template <class Epi, class Sched, bool ALIGN_EPI = false, bool SP2 = false>
; __device__ __forceinline__ void gemm_phase(PG8_LAS unsigned char* lds, const Gemm g, const Sched& S, const Epi& E, const int tid_in) {
;     ...
;             PG8_LDA(At, 1, 1); PG8_STAGE(PG8_SB(1, 0), b3, voffB); PG8_STAGE(PG8_SB(1, 1), b3 + hstep, voffB); PG8_STAGE(PG8_SA(1, 0), a3, voffA);
;             PG8_WAIT_V(8); PG8_WAIT_L(0); PG8_BAR; PG8_MMA(1, 0, At, B0); PG8_MMA(1, 1, At, B1); PG8_BAR; PG8_SCHED;
	s_add_i32 s18, s70, s29
	v_lshl_add_u64 v[140:141], v[140:141], 0, s[44:45]
	s_mov_b32 m0, s18
	ds_read_b128 v[178:181], v145 offset:49152
	ds_read_b128 v[182:185], v145 offset:50176
	ds_read_b128 v[186:189], v145 offset:51200
	ds_read_b128 v[190:193], v145 offset:52224
	ds_read_b128 v[194:197], v145 offset:53248
	ds_read_b128 v[198:201], v145 offset:54272
	ds_read_b128 v[202:205], v145 offset:55296
	ds_read_b128 v[206:209], v145 offset:56320
	global_load_lds_dwordx4 v[140:141], off
	s_add_i32 m0, s18, 0x2000
	s_add_u32 s18, s22, 0xb0080
	v_lshl_add_u64 v[140:141], v[210:211], 0, s[44:45]
	s_addc_u32 s19, s23, 0
	s_add_i32 s22, s71, s29
	global_load_lds_dwordx4 v[140:141], off
	v_lshl_add_u64 v[140:141], s[18:19], 0, v[0:1]
	s_mov_b32 m0, s22
	s_nop 0
	global_load_lds_dwordx4 v[140:141], off
	v_lshl_add_u64 v[140:141], s[18:19], 0, v[134:135]
	s_add_i32 m0, s22, 0x2000
	s_nop 0
	global_load_lds_dwordx4 v[140:141], off
	v_lshl_add_u64 v[140:141], v[212:213], 0, s[44:45]
	s_mov_b32 m0, s38
	s_nop 0
	global_load_lds_dwordx4 v[140:141], off
	v_lshl_add_u64 v[140:141], v[214:215], 0, s[44:45]
	s_mov_b32 m0, s42
	s_nop 0
	global_load_lds_dwordx4 v[140:141], off
	s_waitcnt vmcnt(8)
	s_waitcnt lgkmcnt(0)
	s_barrier
	s_setprio 1
	s_waitcnt lgkmcnt(0)
	v_mfma_f32_16x16x32_bf16 v[62:65], v[146:149], v[178:181], v[62:65]
	v_mfma_f32_16x16x32_bf16 v[58:61], v[154:157], v[178:181], v[58:61]
	v_mfma_f32_16x16x32_bf16 v[54:57], v[146:149], v[186:189], v[54:57]
	v_mfma_f32_16x16x32_bf16 v[46:49], v[154:157], v[186:189], v[46:49]
	v_mfma_f32_16x16x32_bf16 v[38:41], v[146:149], v[194:197], v[38:41]
	v_mfma_f32_16x16x32_bf16 v[30:33], v[154:157], v[194:197], v[30:33]
	v_mfma_f32_16x16x32_bf16 v[22:25], v[146:149], v[202:205], v[22:25]
	v_mfma_f32_16x16x32_bf16 v[14:17], v[154:157], v[202:205], v[14:17]
	v_mfma_f32_16x16x32_bf16 v[62:65], v[150:153], v[182:185], v[62:65]
	v_mfma_f32_16x16x32_bf16 v[58:61], v[158:161], v[182:185], v[58:61]
	v_mfma_f32_16x16x32_bf16 v[54:57], v[150:153], v[190:193], v[54:57]
	v_mfma_f32_16x16x32_bf16 v[46:49], v[158:161], v[190:193], v[46:49]
	v_mfma_f32_16x16x32_bf16 v[38:41], v[150:153], v[198:201], v[38:41]
	v_mfma_f32_16x16x32_bf16 v[30:33], v[158:161], v[198:201], v[30:33]
	v_mfma_f32_16x16x32_bf16 v[22:25], v[150:153], v[206:209], v[22:25]
	v_mfma_f32_16x16x32_bf16 v[14:17], v[158:161], v[206:209], v[14:17]
	s_setprio 0
	s_setprio 1
	v_mfma_f32_16x16x32_bf16 v[50:53], v[162:165], v[178:181], v[50:53]
	v_mfma_f32_16x16x32_bf16 v[42:45], v[170:173], v[178:181], v[42:45]
	v_mfma_f32_16x16x32_bf16 v[34:37], v[162:165], v[186:189], v[34:37]
	v_mfma_f32_16x16x32_bf16 v[26:29], v[170:173], v[186:189], v[26:29]
	v_mfma_f32_16x16x32_bf16 v[18:21], v[162:165], v[194:197], v[18:21]
	v_mfma_f32_16x16x32_bf16 v[10:13], v[170:173], v[194:197], v[10:13]
	v_mfma_f32_16x16x32_bf16 v[6:9], v[162:165], v[202:205], v[6:9]
	v_mfma_f32_16x16x32_bf16 v[2:5], v[170:173], v[202:205], v[2:5]
	v_mfma_f32_16x16x32_bf16 v[50:53], v[166:169], v[182:185], v[50:53]
	v_mfma_f32_16x16x32_bf16 v[42:45], v[174:177], v[182:185], v[42:45]
	v_mfma_f32_16x16x32_bf16 v[34:37], v[166:169], v[190:193], v[34:37]
	v_mfma_f32_16x16x32_bf16 v[26:29], v[174:177], v[190:193], v[26:29]
	v_mfma_f32_16x16x32_bf16 v[18:21], v[166:169], v[198:201], v[18:21]
	v_mfma_f32_16x16x32_bf16 v[10:13], v[174:177], v[198:201], v[10:13]
	v_mfma_f32_16x16x32_bf16 v[6:9], v[166:169], v[206:209], v[6:9]
	v_mfma_f32_16x16x32_bf16 v[2:5], v[174:177], v[206:209], v[2:5]
	s_setprio 0
	s_barrier
	s_add_i32 s64, s64, 2
	s_add_u32 s62, s62, 0x100
	s_addc_u32 s63, s63, 0
	s_cmp_gt_u32 s64, 41
	s_mov_b64 s[18:19], s[20:21]
	s_cbranch_scc0 .LBB0_703
	s_and_b64 vcc, exec, s[14:15]
	s_cbranch_vccz .LBB0_706
	s_barrier
